# non-temporal hint on the WIN epilogue stores (outputs consumed once after the grid barrier)
# baseline (speedup 1.0000x reference)
.LBB0_1050:
	v_mov_b32_e32 v182, v179
	v_mov_b32_e32 v183, v178
	s_cmp_lg_u32 s41, 1
	s_cselect_b32 s2, s41, 0
	v_lshlrev_b32_e32 v151, 3, v182
	v_add_u32_e32 v149, s54, v183
	v_add_u32_e32 v148, s55, v151
	s_cmp_lt_i32 s2, 3
	s_mov_b64 s[0:1], -1
	s_cbranch_scc1 .LBB0_1113
	s_cmp_lt_i32 s2, 5
	s_cbranch_scc1 .LBB0_1055
	s_cmp_eq_u32 s2, 5
	s_cbranch_scc0 .LBB0_1054
	s_lshl_b32 s1, s69, 8
	s_ashr_i32 s0, s69, 4
	s_and_b32 s1, s1, 0xf00
	s_mul_i32 s0, s0, 12
	s_lshl_b32 s3, s71, 2
	v_add_u32_e32 v0, s1, v148
	s_add_i32 s0, s0, s3
	v_ashrrev_i32_e32 v130, 5, v0
	v_ashrrev_i32_e32 v0, 6, v149
	v_ashrrev_i32_e32 v131, 31, v130
	v_add_u32_e32 v132, s0, v0
	v_lshlrev_b64 v[130:131], 12, v[130:131]
	v_ashrrev_i32_e32 v133, 31, v132
	v_lshl_add_u64 v[130:131], s[26:27], 0, v[130:131]
	v_lshlrev_b64 v[132:133], 19, v[132:133]
	v_lshlrev_b32_e32 v0, 6, v183
	v_and_b32_e32 v136, 24, v151
	v_lshl_add_u64 v[132:133], v[130:131], 0, v[132:133]
	v_and_b32_e32 v0, 0xfc0, v0
	v_lshl_add_u64 v[134:135], v[132:133], 0, v[0:1]
	v_lshlrev_b32_e32 v132, 1, v136
	v_mov_b32_e32 v133, v1
	v_lshl_add_u64 v[152:153], v[134:135], 0, v[132:133]
	s_movk_i32 s1, 0x4000
	v_cvt_pk_bf16_f32 v134, v126, v127
	v_cvt_pk_bf16_f32 v135, v128, v129
	v_cvt_pk_bf16_f32 v136, v122, v123
	v_cvt_pk_bf16_f32 v137, v124, v125
	flat_store_dwordx4 v[152:153], v[134:137] nt
	v_add_co_u32_e32 v152, vcc, s1, v152
	s_nop 0
	v_cvt_pk_bf16_f32 v136, v90, v91
	v_cvt_pk_bf16_f32 v134, v94, v95
	v_cvt_pk_bf16_f32 v135, v96, v97
	v_cvt_pk_bf16_f32 v137, v92, v93
	s_nop 0
	v_addc_co_u32_e32 v153, vcc, 0, v153, vcc
	flat_store_dwordx4 v[152:153], v[134:137] nt
	s_nop 1
	v_add_u32_e32 v136, 16, v149
	v_ashrrev_i32_e32 v134, 6, v136
	v_add_u32_e32 v134, s0, v134
	v_ashrrev_i32_e32 v135, 31, v134
	v_lshlrev_b64 v[134:135], 19, v[134:135]
	v_lshlrev_b32_e32 v136, 6, v136
	v_lshl_add_u64 v[134:135], v[130:131], 0, v[134:135]
	v_and_b32_e32 v136, 0xfc0, v136
	v_mov_b32_e32 v137, v1
	v_lshl_add_u64 v[134:135], v[134:135], 0, v[136:137]
	v_lshl_add_u64 v[152:153], v[134:135], 0, v[132:133]
	v_cvt_pk_bf16_f32 v134, v118, v119
	v_cvt_pk_bf16_f32 v135, v120, v121
	v_cvt_pk_bf16_f32 v136, v114, v115
	v_cvt_pk_bf16_f32 v137, v116, v117
	flat_store_dwordx4 v[152:153], v[134:137] nt
	v_add_co_u32_e32 v152, vcc, s1, v152
	s_nop 0
	v_cvt_pk_bf16_f32 v136, v82, v83
	v_cvt_pk_bf16_f32 v134, v86, v87
	v_cvt_pk_bf16_f32 v135, v88, v89
	v_cvt_pk_bf16_f32 v137, v84, v85
	s_nop 0
	v_addc_co_u32_e32 v153, vcc, 0, v153, vcc
	flat_store_dwordx4 v[152:153], v[134:137] nt
	s_nop 1
	v_add_u32_e32 v136, 32, v149
	v_ashrrev_i32_e32 v134, 6, v136
	v_add_u32_e32 v134, s0, v134
	v_ashrrev_i32_e32 v135, 31, v134
	v_lshlrev_b64 v[134:135], 19, v[134:135]
	v_lshlrev_b32_e32 v136, 6, v136
	v_lshl_add_u64 v[134:135], v[130:131], 0, v[134:135]
	v_and_b32_e32 v136, 0xfc0, v136
	v_mov_b32_e32 v137, v1
	v_lshl_add_u64 v[134:135], v[134:135], 0, v[136:137]
	v_lshl_add_u64 v[152:153], v[134:135], 0, v[132:133]
	v_cvt_pk_bf16_f32 v134, v110, v111
	v_cvt_pk_bf16_f32 v135, v112, v113
	v_cvt_pk_bf16_f32 v136, v106, v107
	v_cvt_pk_bf16_f32 v137, v108, v109
	flat_store_dwordx4 v[152:153], v[134:137] nt
	v_add_co_u32_e32 v152, vcc, s1, v152
	s_nop 0
	v_cvt_pk_bf16_f32 v136, v74, v75
	v_cvt_pk_bf16_f32 v134, v78, v79
	v_cvt_pk_bf16_f32 v135, v80, v81
	v_cvt_pk_bf16_f32 v137, v76, v77
	s_nop 0
	v_addc_co_u32_e32 v153, vcc, 0, v153, vcc
	flat_store_dwordx4 v[152:153], v[134:137] nt
	s_nop 1
	v_add_u32_e32 v136, 48, v149
	v_ashrrev_i32_e32 v134, 6, v136
	v_add_u32_e32 v134, s0, v134
	v_ashrrev_i32_e32 v135, 31, v134
	v_lshlrev_b64 v[134:135], 19, v[134:135]
	v_lshlrev_b32_e32 v136, 6, v136
	v_lshl_add_u64 v[134:135], v[130:131], 0, v[134:135]
	v_and_b32_e32 v136, 0xfc0, v136
	v_mov_b32_e32 v137, v1
	v_lshl_add_u64 v[134:135], v[134:135], 0, v[136:137]
	v_lshl_add_u64 v[152:153], v[134:135], 0, v[132:133]
	v_cvt_pk_bf16_f32 v134, v102, v103
	v_cvt_pk_bf16_f32 v135, v104, v105
	v_cvt_pk_bf16_f32 v136, v98, v99
	v_cvt_pk_bf16_f32 v137, v100, v101
	flat_store_dwordx4 v[152:153], v[134:137] nt
	v_add_co_u32_e32 v152, vcc, s1, v152
	s_nop 0
	v_cvt_pk_bf16_f32 v134, v70, v71
	v_cvt_pk_bf16_f32 v135, v72, v73
	v_cvt_pk_bf16_f32 v136, v66, v67
	v_cvt_pk_bf16_f32 v137, v68, v69
	s_nop 0
	v_addc_co_u32_e32 v153, vcc, 0, v153, vcc
	flat_store_dwordx4 v[152:153], v[134:137] nt
	s_nop 1
	v_add_u32_e32 v134, 0x80, v149
	v_ashrrev_i32_e32 v134, 6, v134
	v_add_u32_e32 v134, s0, v134
	v_ashrrev_i32_e32 v135, 31, v134
	v_lshlrev_b64 v[134:135], 19, v[134:135]
	v_lshl_add_u64 v[134:135], v[130:131], 0, v[134:135]
	v_lshl_add_u64 v[134:135], v[134:135], 0, v[0:1]
	v_lshl_add_u64 v[152:153], v[134:135], 0, v[132:133]
	v_cvt_pk_bf16_f32 v134, v62, v63
	v_cvt_pk_bf16_f32 v135, v64, v65
	v_cvt_pk_bf16_f32 v136, v58, v59
	v_cvt_pk_bf16_f32 v137, v60, v61
	flat_store_dwordx4 v[152:153], v[134:137] nt
	v_add_co_u32_e32 v152, vcc, s1, v152
	s_nop 0
	v_cvt_pk_bf16_f32 v134, v30, v31
	v_add_u32_e32 v0, 0x90, v149
	v_addc_co_u32_e32 v153, vcc, 0, v153, vcc
	v_cvt_pk_bf16_f32 v135, v32, v33
	v_cvt_pk_bf16_f32 v136, v26, v27
	v_cvt_pk_bf16_f32 v137, v28, v29
	flat_store_dwordx4 v[152:153], v[134:137] nt
	s_nop 1
	v_ashrrev_i32_e32 v134, 6, v0
	v_add_u32_e32 v134, s0, v134
	v_ashrrev_i32_e32 v135, 31, v134
	v_lshlrev_b64 v[134:135], 19, v[134:135]
	v_lshlrev_b32_e32 v0, 6, v0
	v_lshl_add_u64 v[134:135], v[130:131], 0, v[134:135]
	v_and_b32_e32 v0, 0xfc0, v0
	v_lshl_add_u64 v[134:135], v[134:135], 0, v[0:1]
	v_lshl_add_u64 v[152:153], v[134:135], 0, v[132:133]
	v_cvt_pk_bf16_f32 v134, v54, v55
	v_cvt_pk_bf16_f32 v135, v56, v57
	v_cvt_pk_bf16_f32 v136, v50, v51
	v_cvt_pk_bf16_f32 v137, v52, v53
	flat_store_dwordx4 v[152:153], v[134:137] nt
	v_add_co_u32_e32 v152, vcc, s1, v152
	s_nop 0
	v_cvt_pk_bf16_f32 v134, v22, v23
	v_add_u32_e32 v0, 0xa0, v149
	v_addc_co_u32_e32 v153, vcc, 0, v153, vcc
	v_cvt_pk_bf16_f32 v135, v24, v25
	v_cvt_pk_bf16_f32 v136, v18, v19
	v_cvt_pk_bf16_f32 v137, v20, v21
	flat_store_dwordx4 v[152:153], v[134:137] nt
	s_nop 1
	v_ashrrev_i32_e32 v134, 6, v0
	v_add_u32_e32 v134, s0, v134
	v_ashrrev_i32_e32 v135, 31, v134
	v_lshlrev_b64 v[134:135], 19, v[134:135]
	v_lshlrev_b32_e32 v0, 6, v0
	v_lshl_add_u64 v[134:135], v[130:131], 0, v[134:135]
	v_and_b32_e32 v0, 0xfc0, v0
	v_lshl_add_u64 v[134:135], v[134:135], 0, v[0:1]
	v_lshl_add_u64 v[152:153], v[134:135], 0, v[132:133]
	v_cvt_pk_bf16_f32 v134, v46, v47
	v_cvt_pk_bf16_f32 v135, v48, v49
	v_cvt_pk_bf16_f32 v136, v42, v43
	v_cvt_pk_bf16_f32 v137, v44, v45
	flat_store_dwordx4 v[152:153], v[134:137] nt
	v_add_co_u32_e32 v152, vcc, s1, v152
	s_nop 0
	v_cvt_pk_bf16_f32 v134, v14, v15
	v_add_u32_e32 v0, 0xb0, v149
	v_addc_co_u32_e32 v153, vcc, 0, v153, vcc
	v_cvt_pk_bf16_f32 v135, v16, v17
	v_cvt_pk_bf16_f32 v136, v10, v11
	v_cvt_pk_bf16_f32 v137, v12, v13
	flat_store_dwordx4 v[152:153], v[134:137] nt
	s_nop 1
	v_ashrrev_i32_e32 v134, 6, v0
	v_add_u32_e32 v134, s0, v134
	v_ashrrev_i32_e32 v135, 31, v134
	v_lshlrev_b64 v[134:135], 19, v[134:135]
	v_lshlrev_b32_e32 v0, 6, v0
	v_lshl_add_u64 v[130:131], v[130:131], 0, v[134:135]
	v_and_b32_e32 v0, 0xfc0, v0
	v_lshl_add_u64 v[130:131], v[130:131], 0, v[0:1]
	v_lshl_add_u64 v[134:135], v[130:131], 0, v[132:133]
	v_cvt_pk_bf16_f32 v130, v38, v39
	v_cvt_pk_bf16_f32 v131, v40, v41
	v_cvt_pk_bf16_f32 v132, v34, v35
	v_cvt_pk_bf16_f32 v133, v36, v37
	flat_store_dwordx4 v[134:135], v[130:133] nt
	v_add_co_u32_e32 v134, vcc, 0x4000, v134
	s_nop 0
	v_cvt_pk_bf16_f32 v130, v6, v7
	v_cvt_pk_bf16_f32 v131, v8, v9
	v_cvt_pk_bf16_f32 v132, v2, v3
	v_cvt_pk_bf16_f32 v133, v4, v5
	s_nop 0
	v_addc_co_u32_e32 v135, vcc, 0, v135, vcc
	flat_store_dwordx4 v[134:135], v[130:133] nt

.LBB0_1055:
	s_andn2_b64 vcc, exec, s[0:1]
	s_cbranch_vccnz .LBB0_1112
	s_lshl_b32 s78, s70, 8
	v_add_u32_e32 v153, s78, v149
	s_lshl_b32 s3, s71, 1
	s_lshr_b32 s37, 0x1000, s3
	s_cmp_eq_u32 s41, 3
	s_mov_b32 s76, 0xa800000
	s_cselect_b32 s76, s76, 0xc000000
	s_cselect_b32 s0, 0x3e38aa3b, 1.0
	v_mov_b32_e32 v150, s0
	s_add_u32 s80, s82, s76
	s_addc_u32 s81, s83, 0
	s_lshl_b32 s77, -1, s3
	s_not_b32 s77, s77
	s_lshl_b32 s76, s71, 2
	s_or_b32 s76, s76, s58
	v_add_u32_e32 v154, s59, v151
	v_ashrrev_i32_e32 v155, 31, v154
	v_lshl_add_u64 v[154:155], v[154:155], 1, s[80:81]
	v_ashrrev_i32_e32 v0, 12, v153
	v_mad_i32_i24 v174, v0, 12, s76
	v_ashrrev_i32_e32 v175, 31, v174
	v_and_b32_e32 v172, s77, v153
	v_mul_u32_u24_e32 v172, s37, v172
	v_and_b32_e32 v173, 0xfff, v153
	v_lshrrev_b32_e32 v173, s3, v173
	v_add_lshl_u32 v0, v172, v173, 7
	v_lshl_add_u64 v[130:131], v[154:155], 0, v[0:1]
	v_lshlrev_b64 v[174:175], 19, v[174:175]
	v_lshl_add_u64 v[130:131], v[130:131], 0, v[174:175]
	s_lshr_b32 s6, 0x800, s3
	s_mov_b32 s7, 0
	s_mul_i32 s0, s6, 5
	s_mov_b32 s1, 0
	s_mov_b32 s80, 0x100000
	s_mov_b32 s81, 0
	s_and_b64 vcc, exec, s[22:23]
	s_cbranch_vccz .Lqk_nonrot
	v_cmp_eq_u32_e32 vcc, 0, v182
	v_cmp_gt_i32_e64 s[76:77], 2, v182
	s_nop 0
	v_cndmask_b32_e64 v0, 1.0, -1.0, vcc
	v_cndmask_b32_e64 v152, 0, v0, s[76:77]
	v_add_u32_e32 v134, s60, v153
	v_ashrrev_i32_e32 v135, 31, v134
	v_lshlrev_b64 v[134:135], 6, v[134:135]
	v_lshl_add_u64 v[134:135], s[20:21], 0, v[134:135]
	v_add_co_u32_e32 v136, vcc, 0x2000, v134
	s_nop 1
	v_addc_co_u32_e32 v137, vcc, 0, v135, vcc
	v_cmp_lt_i32_e32 vcc, v221, v223
	s_nop 1
	v_cndmask_b32_e32 v0, v219, v221, vcc
	v_lshlrev_b32_e32 v0, 2, v0
	global_load_dwordx4 v[154:157], v[134:135], off offset:0
	global_load_dwordx4 v[158:161], v[134:135], off offset:16
	global_load_dwordx4 v[162:165], v[134:135], off offset:32
	global_load_dwordx4 v[166:169], v[134:135], off offset:48
	s_waitcnt vmcnt(0)
	v_cndmask_b32_e64 v154, 1.0, v154, s[76:77]
	v_cndmask_b32_e64 v155, 1.0, v155, s[76:77]
	v_cndmask_b32_e64 v156, 1.0, v156, s[76:77]
	v_cndmask_b32_e64 v157, 1.0, v157, s[76:77]
	v_cndmask_b32_e64 v158, 1.0, v158, s[76:77]
	v_cndmask_b32_e64 v159, 1.0, v159, s[76:77]
	v_cndmask_b32_e64 v160, 1.0, v160, s[76:77]
	v_cndmask_b32_e64 v161, 1.0, v161, s[76:77]
	v_pk_mul_f32 v[162:163], v[152:153], v[162:163] op_sel_hi:[0,1]
	v_pk_mul_f32 v[164:165], v[152:153], v[164:165] op_sel_hi:[0,1]
	v_pk_mul_f32 v[166:167], v[152:153], v[166:167] op_sel_hi:[0,1]
	v_pk_mul_f32 v[168:169], v[152:153], v[168:169] op_sel_hi:[0,1]
	ds_bpermute_b32 v170, v0, v126
	ds_bpermute_b32 v171, v0, v127
	ds_bpermute_b32 v172, v0, v128
	ds_bpermute_b32 v173, v0, v129
	ds_bpermute_b32 v174, v0, v122
	ds_bpermute_b32 v175, v0, v123
	ds_bpermute_b32 v176, v0, v124
	ds_bpermute_b32 v177, v0, v125
	s_waitcnt lgkmcnt(0)
	v_pk_mul_f32 v[170:171], v[162:163], v[170:171]
	v_pk_mul_f32 v[172:173], v[164:165], v[172:173]
	v_pk_mul_f32 v[174:175], v[166:167], v[174:175]
	v_pk_mul_f32 v[176:177], v[168:169], v[176:177]
	v_pk_fma_f32 v[170:171], v[126:127], v[154:155], v[170:171]
	v_pk_fma_f32 v[172:173], v[128:129], v[156:157], v[172:173]
	v_pk_fma_f32 v[174:175], v[122:123], v[158:159], v[174:175]
	v_pk_fma_f32 v[176:177], v[124:125], v[160:161], v[176:177]
	v_pk_mul_f32 v[170:171], v[150:151], v[170:171] op_sel_hi:[0,1]
	v_pk_mul_f32 v[172:173], v[150:151], v[172:173] op_sel_hi:[0,1]
	v_pk_mul_f32 v[174:175], v[150:151], v[174:175] op_sel_hi:[0,1]
	v_pk_mul_f32 v[176:177], v[150:151], v[176:177] op_sel_hi:[0,1]
	v_cvt_pk_bf16_f32 v170, v170, v171
	v_cvt_pk_bf16_f32 v171, v172, v173
	v_cvt_pk_bf16_f32 v172, v174, v175
	v_cvt_pk_bf16_f32 v173, v176, v177
	global_store_dwordx4 v[130:131], v[170:173], off nt
	v_lshl_add_u64 v[132:133], v[130:131], 0, s[80:81]
	ds_bpermute_b32 v170, v0, v94
	ds_bpermute_b32 v171, v0, v95
	ds_bpermute_b32 v172, v0, v96
	ds_bpermute_b32 v173, v0, v97
	ds_bpermute_b32 v174, v0, v90
	ds_bpermute_b32 v175, v0, v91
	ds_bpermute_b32 v176, v0, v92
	ds_bpermute_b32 v177, v0, v93
	s_waitcnt lgkmcnt(0)
	v_pk_mul_f32 v[170:171], v[162:163], v[170:171]
	v_pk_mul_f32 v[172:173], v[164:165], v[172:173]
	v_pk_mul_f32 v[174:175], v[166:167], v[174:175]
	v_pk_mul_f32 v[176:177], v[168:169], v[176:177]
	v_pk_fma_f32 v[170:171], v[94:95], v[154:155], v[170:171]
	v_pk_fma_f32 v[172:173], v[96:97], v[156:157], v[172:173]
	v_pk_fma_f32 v[174:175], v[90:91], v[158:159], v[174:175]
	v_pk_fma_f32 v[176:177], v[92:93], v[160:161], v[176:177]
	v_pk_mul_f32 v[170:171], v[150:151], v[170:171] op_sel_hi:[0,1]
	v_pk_mul_f32 v[172:173], v[150:151], v[172:173] op_sel_hi:[0,1]
	v_pk_mul_f32 v[174:175], v[150:151], v[174:175] op_sel_hi:[0,1]
	v_pk_mul_f32 v[176:177], v[150:151], v[176:177] op_sel_hi:[0,1]
	v_cvt_pk_bf16_f32 v170, v170, v171
	v_cvt_pk_bf16_f32 v171, v172, v173
	v_cvt_pk_bf16_f32 v172, v174, v175
	v_cvt_pk_bf16_f32 v173, v176, v177
	global_store_dwordx4 v[132:133], v[170:173], off nt
	v_lshl_add_u64 v[130:131], v[130:131], 0, s[6:7]
	global_load_dwordx4 v[126:129], v[134:135], off offset:1024
	global_load_dwordx4 v[122:125], v[134:135], off offset:1040
	global_load_dwordx4 v[94:97], v[134:135], off offset:1056
	global_load_dwordx4 v[90:93], v[134:135], off offset:1072
	global_load_dwordx4 v[154:157], v[134:135], off offset:2048
	global_load_dwordx4 v[158:161], v[134:135], off offset:2064
	global_load_dwordx4 v[162:165], v[134:135], off offset:2080
	global_load_dwordx4 v[166:169], v[134:135], off offset:2096
	s_waitcnt vmcnt(4)
	v_cndmask_b32_e64 v126, 1.0, v126, s[76:77]
	v_cndmask_b32_e64 v127, 1.0, v127, s[76:77]
	v_cndmask_b32_e64 v128, 1.0, v128, s[76:77]
	v_cndmask_b32_e64 v129, 1.0, v129, s[76:77]
	v_cndmask_b32_e64 v122, 1.0, v122, s[76:77]
	v_cndmask_b32_e64 v123, 1.0, v123, s[76:77]
	v_cndmask_b32_e64 v124, 1.0, v124, s[76:77]
	v_cndmask_b32_e64 v125, 1.0, v125, s[76:77]
	v_pk_mul_f32 v[94:95], v[152:153], v[94:95] op_sel_hi:[0,1]
	v_pk_mul_f32 v[96:97], v[152:153], v[96:97] op_sel_hi:[0,1]
	v_pk_mul_f32 v[90:91], v[152:153], v[90:91] op_sel_hi:[0,1]
	v_pk_mul_f32 v[92:93], v[152:153], v[92:93] op_sel_hi:[0,1]
	ds_bpermute_b32 v170, v0, v118
	ds_bpermute_b32 v171, v0, v119
	ds_bpermute_b32 v172, v0, v120
	ds_bpermute_b32 v173, v0, v121
	ds_bpermute_b32 v174, v0, v114
	ds_bpermute_b32 v175, v0, v115
	ds_bpermute_b32 v176, v0, v116
	ds_bpermute_b32 v177, v0, v117
	s_waitcnt lgkmcnt(0)
	v_pk_mul_f32 v[170:171], v[94:95], v[170:171]
	v_pk_mul_f32 v[172:173], v[96:97], v[172:173]
	v_pk_mul_f32 v[174:175], v[90:91], v[174:175]
	v_pk_mul_f32 v[176:177], v[92:93], v[176:177]
	v_pk_fma_f32 v[170:171], v[118:119], v[126:127], v[170:171]
	v_pk_fma_f32 v[172:173], v[120:121], v[128:129], v[172:173]
	v_pk_fma_f32 v[174:175], v[114:115], v[122:123], v[174:175]
	v_pk_fma_f32 v[176:177], v[116:117], v[124:125], v[176:177]
	v_pk_mul_f32 v[170:171], v[150:151], v[170:171] op_sel_hi:[0,1]
	v_pk_mul_f32 v[172:173], v[150:151], v[172:173] op_sel_hi:[0,1]
	v_pk_mul_f32 v[174:175], v[150:151], v[174:175] op_sel_hi:[0,1]
	v_pk_mul_f32 v[176:177], v[150:151], v[176:177] op_sel_hi:[0,1]
	v_cvt_pk_bf16_f32 v170, v170, v171
	v_cvt_pk_bf16_f32 v171, v172, v173
	v_cvt_pk_bf16_f32 v172, v174, v175
	v_cvt_pk_bf16_f32 v173, v176, v177
	global_store_dwordx4 v[130:131], v[170:173], off nt
	v_lshl_add_u64 v[132:133], v[130:131], 0, s[80:81]
	ds_bpermute_b32 v170, v0, v86
	ds_bpermute_b32 v171, v0, v87
	ds_bpermute_b32 v172, v0, v88
	ds_bpermute_b32 v173, v0, v89
	ds_bpermute_b32 v174, v0, v82
	ds_bpermute_b32 v175, v0, v83
	ds_bpermute_b32 v176, v0, v84
	ds_bpermute_b32 v177, v0, v85
	s_waitcnt lgkmcnt(0)
	v_pk_mul_f32 v[170:171], v[94:95], v[170:171]
	v_pk_mul_f32 v[172:173], v[96:97], v[172:173]
	v_pk_mul_f32 v[174:175], v[90:91], v[174:175]
	v_pk_mul_f32 v[176:177], v[92:93], v[176:177]
	v_pk_fma_f32 v[170:171], v[86:87], v[126:127], v[170:171]
	v_pk_fma_f32 v[172:173], v[88:89], v[128:129], v[172:173]
	v_pk_fma_f32 v[174:175], v[82:83], v[122:123], v[174:175]
	v_pk_fma_f32 v[176:177], v[84:85], v[124:125], v[176:177]
	v_pk_mul_f32 v[170:171], v[150:151], v[170:171] op_sel_hi:[0,1]
	v_pk_mul_f32 v[172:173], v[150:151], v[172:173] op_sel_hi:[0,1]
	v_pk_mul_f32 v[174:175], v[150:151], v[174:175] op_sel_hi:[0,1]
	v_pk_mul_f32 v[176:177], v[150:151], v[176:177] op_sel_hi:[0,1]
	v_cvt_pk_bf16_f32 v170, v170, v171
	v_cvt_pk_bf16_f32 v171, v172, v173
	v_cvt_pk_bf16_f32 v172, v174, v175
	v_cvt_pk_bf16_f32 v173, v176, v177
	global_store_dwordx4 v[132:133], v[170:173], off nt
	v_lshl_add_u64 v[130:131], v[130:131], 0, s[6:7]
	global_load_dwordx4 v[126:129], v[134:135], off offset:3072
	global_load_dwordx4 v[122:125], v[134:135], off offset:3088
	global_load_dwordx4 v[94:97], v[134:135], off offset:3104
	global_load_dwordx4 v[90:93], v[134:135], off offset:3120
	s_waitcnt vmcnt(6)
	v_cndmask_b32_e64 v154, 1.0, v154, s[76:77]
	v_cndmask_b32_e64 v155, 1.0, v155, s[76:77]
	v_cndmask_b32_e64 v156, 1.0, v156, s[76:77]
	v_cndmask_b32_e64 v157, 1.0, v157, s[76:77]
	v_cndmask_b32_e64 v158, 1.0, v158, s[76:77]
	v_cndmask_b32_e64 v159, 1.0, v159, s[76:77]
	v_cndmask_b32_e64 v160, 1.0, v160, s[76:77]
	v_cndmask_b32_e64 v161, 1.0, v161, s[76:77]
	v_pk_mul_f32 v[162:163], v[152:153], v[162:163] op_sel_hi:[0,1]
	v_pk_mul_f32 v[164:165], v[152:153], v[164:165] op_sel_hi:[0,1]
	v_pk_mul_f32 v[166:167], v[152:153], v[166:167] op_sel_hi:[0,1]
	v_pk_mul_f32 v[168:169], v[152:153], v[168:169] op_sel_hi:[0,1]
	ds_bpermute_b32 v170, v0, v110
	ds_bpermute_b32 v171, v0, v111
	ds_bpermute_b32 v172, v0, v112
	ds_bpermute_b32 v173, v0, v113
	ds_bpermute_b32 v174, v0, v106
	ds_bpermute_b32 v175, v0, v107
	ds_bpermute_b32 v176, v0, v108
	ds_bpermute_b32 v177, v0, v109
	s_waitcnt lgkmcnt(0)
	v_pk_mul_f32 v[170:171], v[162:163], v[170:171]
	v_pk_mul_f32 v[172:173], v[164:165], v[172:173]
	v_pk_mul_f32 v[174:175], v[166:167], v[174:175]
	v_pk_mul_f32 v[176:177], v[168:169], v[176:177]
	v_pk_fma_f32 v[170:171], v[110:111], v[154:155], v[170:171]
	v_pk_fma_f32 v[172:173], v[112:113], v[156:157], v[172:173]
	v_pk_fma_f32 v[174:175], v[106:107], v[158:159], v[174:175]
	v_pk_fma_f32 v[176:177], v[108:109], v[160:161], v[176:177]
	v_pk_mul_f32 v[170:171], v[150:151], v[170:171] op_sel_hi:[0,1]
	v_pk_mul_f32 v[172:173], v[150:151], v[172:173] op_sel_hi:[0,1]
	v_pk_mul_f32 v[174:175], v[150:151], v[174:175] op_sel_hi:[0,1]
	v_pk_mul_f32 v[176:177], v[150:151], v[176:177] op_sel_hi:[0,1]
	v_cvt_pk_bf16_f32 v170, v170, v171
	v_cvt_pk_bf16_f32 v171, v172, v173
	v_cvt_pk_bf16_f32 v172, v174, v175
	v_cvt_pk_bf16_f32 v173, v176, v177
	global_store_dwordx4 v[130:131], v[170:173], off nt
	v_lshl_add_u64 v[132:133], v[130:131], 0, s[80:81]
	ds_bpermute_b32 v170, v0, v78
	ds_bpermute_b32 v171, v0, v79
	ds_bpermute_b32 v172, v0, v80
	ds_bpermute_b32 v173, v0, v81
	ds_bpermute_b32 v174, v0, v74
	ds_bpermute_b32 v175, v0, v75
	ds_bpermute_b32 v176, v0, v76
	ds_bpermute_b32 v177, v0, v77
	s_waitcnt lgkmcnt(0)
	v_pk_mul_f32 v[170:171], v[162:163], v[170:171]
	v_pk_mul_f32 v[172:173], v[164:165], v[172:173]
	v_pk_mul_f32 v[174:175], v[166:167], v[174:175]
	v_pk_mul_f32 v[176:177], v[168:169], v[176:177]
	v_pk_fma_f32 v[170:171], v[78:79], v[154:155], v[170:171]
	v_pk_fma_f32 v[172:173], v[80:81], v[156:157], v[172:173]
	v_pk_fma_f32 v[174:175], v[74:75], v[158:159], v[174:175]
	v_pk_fma_f32 v[176:177], v[76:77], v[160:161], v[176:177]
	v_pk_mul_f32 v[170:171], v[150:151], v[170:171] op_sel_hi:[0,1]
	v_pk_mul_f32 v[172:173], v[150:151], v[172:173] op_sel_hi:[0,1]
	v_pk_mul_f32 v[174:175], v[150:151], v[174:175] op_sel_hi:[0,1]
	v_pk_mul_f32 v[176:177], v[150:151], v[176:177] op_sel_hi:[0,1]
	v_cvt_pk_bf16_f32 v170, v170, v171
	v_cvt_pk_bf16_f32 v171, v172, v173
	v_cvt_pk_bf16_f32 v172, v174, v175
	v_cvt_pk_bf16_f32 v173, v176, v177
	global_store_dwordx4 v[132:133], v[170:173], off nt
	v_lshl_add_u64 v[130:131], v[130:131], 0, s[6:7]
	global_load_dwordx4 v[154:157], v[136:137], off offset:0
	global_load_dwordx4 v[158:161], v[136:137], off offset:16
	global_load_dwordx4 v[162:165], v[136:137], off offset:32
	global_load_dwordx4 v[166:169], v[136:137], off offset:48
	s_waitcnt vmcnt(6)
	v_cndmask_b32_e64 v126, 1.0, v126, s[76:77]
	v_cndmask_b32_e64 v127, 1.0, v127, s[76:77]
	v_cndmask_b32_e64 v128, 1.0, v128, s[76:77]
	v_cndmask_b32_e64 v129, 1.0, v129, s[76:77]
	v_cndmask_b32_e64 v122, 1.0, v122, s[76:77]
	v_cndmask_b32_e64 v123, 1.0, v123, s[76:77]
	v_cndmask_b32_e64 v124, 1.0, v124, s[76:77]
	v_cndmask_b32_e64 v125, 1.0, v125, s[76:77]
	v_pk_mul_f32 v[94:95], v[152:153], v[94:95] op_sel_hi:[0,1]
	v_pk_mul_f32 v[96:97], v[152:153], v[96:97] op_sel_hi:[0,1]
	v_pk_mul_f32 v[90:91], v[152:153], v[90:91] op_sel_hi:[0,1]
	v_pk_mul_f32 v[92:93], v[152:153], v[92:93] op_sel_hi:[0,1]
	ds_bpermute_b32 v170, v0, v102
	ds_bpermute_b32 v171, v0, v103
	ds_bpermute_b32 v172, v0, v104
	ds_bpermute_b32 v173, v0, v105
	ds_bpermute_b32 v174, v0, v98
	ds_bpermute_b32 v175, v0, v99
	ds_bpermute_b32 v176, v0, v100
	ds_bpermute_b32 v177, v0, v101
	s_waitcnt lgkmcnt(0)
	v_pk_mul_f32 v[170:171], v[94:95], v[170:171]
	v_pk_mul_f32 v[172:173], v[96:97], v[172:173]
	v_pk_mul_f32 v[174:175], v[90:91], v[174:175]
	v_pk_mul_f32 v[176:177], v[92:93], v[176:177]
	v_pk_fma_f32 v[170:171], v[102:103], v[126:127], v[170:171]
	v_pk_fma_f32 v[172:173], v[104:105], v[128:129], v[172:173]
	v_pk_fma_f32 v[174:175], v[98:99], v[122:123], v[174:175]
	v_pk_fma_f32 v[176:177], v[100:101], v[124:125], v[176:177]
	v_pk_mul_f32 v[170:171], v[150:151], v[170:171] op_sel_hi:[0,1]
	v_pk_mul_f32 v[172:173], v[150:151], v[172:173] op_sel_hi:[0,1]
	v_pk_mul_f32 v[174:175], v[150:151], v[174:175] op_sel_hi:[0,1]
	v_pk_mul_f32 v[176:177], v[150:151], v[176:177] op_sel_hi:[0,1]
	v_cvt_pk_bf16_f32 v170, v170, v171
	v_cvt_pk_bf16_f32 v171, v172, v173
	v_cvt_pk_bf16_f32 v172, v174, v175
	v_cvt_pk_bf16_f32 v173, v176, v177
	global_store_dwordx4 v[130:131], v[170:173], off nt
	v_lshl_add_u64 v[132:133], v[130:131], 0, s[80:81]
	ds_bpermute_b32 v170, v0, v70
	ds_bpermute_b32 v171, v0, v71
	ds_bpermute_b32 v172, v0, v72
	ds_bpermute_b32 v173, v0, v73
	ds_bpermute_b32 v174, v0, v66
	ds_bpermute_b32 v175, v0, v67
	ds_bpermute_b32 v176, v0, v68
	ds_bpermute_b32 v177, v0, v69
	s_waitcnt lgkmcnt(0)
	v_pk_mul_f32 v[170:171], v[94:95], v[170:171]
	v_pk_mul_f32 v[172:173], v[96:97], v[172:173]
	v_pk_mul_f32 v[174:175], v[90:91], v[174:175]
	v_pk_mul_f32 v[176:177], v[92:93], v[176:177]
	v_pk_fma_f32 v[170:171], v[70:71], v[126:127], v[170:171]
	v_pk_fma_f32 v[172:173], v[72:73], v[128:129], v[172:173]
	v_pk_fma_f32 v[174:175], v[66:67], v[122:123], v[174:175]
	v_pk_fma_f32 v[176:177], v[68:69], v[124:125], v[176:177]
	v_pk_mul_f32 v[170:171], v[150:151], v[170:171] op_sel_hi:[0,1]
	v_pk_mul_f32 v[172:173], v[150:151], v[172:173] op_sel_hi:[0,1]
	v_pk_mul_f32 v[174:175], v[150:151], v[174:175] op_sel_hi:[0,1]
	v_pk_mul_f32 v[176:177], v[150:151], v[176:177] op_sel_hi:[0,1]
	v_cvt_pk_bf16_f32 v170, v170, v171
	v_cvt_pk_bf16_f32 v171, v172, v173
	v_cvt_pk_bf16_f32 v172, v174, v175
	v_cvt_pk_bf16_f32 v173, v176, v177
	global_store_dwordx4 v[132:133], v[170:173], off nt
	v_lshl_add_u64 v[130:131], v[130:131], 0, s[0:1]
	global_load_dwordx4 v[126:129], v[136:137], off offset:1024
	global_load_dwordx4 v[122:125], v[136:137], off offset:1040
	global_load_dwordx4 v[94:97], v[136:137], off offset:1056
	global_load_dwordx4 v[90:93], v[136:137], off offset:1072
	s_waitcnt vmcnt(6)
	v_cndmask_b32_e64 v154, 1.0, v154, s[76:77]
	v_cndmask_b32_e64 v155, 1.0, v155, s[76:77]
	v_cndmask_b32_e64 v156, 1.0, v156, s[76:77]
	v_cndmask_b32_e64 v157, 1.0, v157, s[76:77]
	v_cndmask_b32_e64 v158, 1.0, v158, s[76:77]
	v_cndmask_b32_e64 v159, 1.0, v159, s[76:77]
	v_cndmask_b32_e64 v160, 1.0, v160, s[76:77]
	v_cndmask_b32_e64 v161, 1.0, v161, s[76:77]
	v_pk_mul_f32 v[162:163], v[152:153], v[162:163] op_sel_hi:[0,1]
	v_pk_mul_f32 v[164:165], v[152:153], v[164:165] op_sel_hi:[0,1]
	v_pk_mul_f32 v[166:167], v[152:153], v[166:167] op_sel_hi:[0,1]
	v_pk_mul_f32 v[168:169], v[152:153], v[168:169] op_sel_hi:[0,1]
	ds_bpermute_b32 v170, v0, v62
	ds_bpermute_b32 v171, v0, v63
	ds_bpermute_b32 v172, v0, v64
	ds_bpermute_b32 v173, v0, v65
	ds_bpermute_b32 v174, v0, v58
	ds_bpermute_b32 v175, v0, v59
	ds_bpermute_b32 v176, v0, v60
	ds_bpermute_b32 v177, v0, v61
	s_waitcnt lgkmcnt(0)
	v_pk_mul_f32 v[170:171], v[162:163], v[170:171]
	v_pk_mul_f32 v[172:173], v[164:165], v[172:173]
	v_pk_mul_f32 v[174:175], v[166:167], v[174:175]
	v_pk_mul_f32 v[176:177], v[168:169], v[176:177]
	v_pk_fma_f32 v[170:171], v[62:63], v[154:155], v[170:171]
	v_pk_fma_f32 v[172:173], v[64:65], v[156:157], v[172:173]
	v_pk_fma_f32 v[174:175], v[58:59], v[158:159], v[174:175]
	v_pk_fma_f32 v[176:177], v[60:61], v[160:161], v[176:177]
	v_pk_mul_f32 v[170:171], v[150:151], v[170:171] op_sel_hi:[0,1]
	v_pk_mul_f32 v[172:173], v[150:151], v[172:173] op_sel_hi:[0,1]
	v_pk_mul_f32 v[174:175], v[150:151], v[174:175] op_sel_hi:[0,1]
	v_pk_mul_f32 v[176:177], v[150:151], v[176:177] op_sel_hi:[0,1]
	v_cvt_pk_bf16_f32 v170, v170, v171
	v_cvt_pk_bf16_f32 v171, v172, v173
	v_cvt_pk_bf16_f32 v172, v174, v175
	v_cvt_pk_bf16_f32 v173, v176, v177
	global_store_dwordx4 v[130:131], v[170:173], off nt
	v_lshl_add_u64 v[132:133], v[130:131], 0, s[80:81]
	ds_bpermute_b32 v170, v0, v30
	ds_bpermute_b32 v171, v0, v31
	ds_bpermute_b32 v172, v0, v32
	ds_bpermute_b32 v173, v0, v33
	ds_bpermute_b32 v174, v0, v26
	ds_bpermute_b32 v175, v0, v27
	ds_bpermute_b32 v176, v0, v28
	ds_bpermute_b32 v177, v0, v29
	s_waitcnt lgkmcnt(0)
	v_pk_mul_f32 v[170:171], v[162:163], v[170:171]
	v_pk_mul_f32 v[172:173], v[164:165], v[172:173]
	v_pk_mul_f32 v[174:175], v[166:167], v[174:175]
	v_pk_mul_f32 v[176:177], v[168:169], v[176:177]
	v_pk_fma_f32 v[170:171], v[30:31], v[154:155], v[170:171]
	v_pk_fma_f32 v[172:173], v[32:33], v[156:157], v[172:173]
	v_pk_fma_f32 v[174:175], v[26:27], v[158:159], v[174:175]
	v_pk_fma_f32 v[176:177], v[28:29], v[160:161], v[176:177]
	v_pk_mul_f32 v[170:171], v[150:151], v[170:171] op_sel_hi:[0,1]
	v_pk_mul_f32 v[172:173], v[150:151], v[172:173] op_sel_hi:[0,1]
	v_pk_mul_f32 v[174:175], v[150:151], v[174:175] op_sel_hi:[0,1]
	v_pk_mul_f32 v[176:177], v[150:151], v[176:177] op_sel_hi:[0,1]
	v_cvt_pk_bf16_f32 v170, v170, v171
	v_cvt_pk_bf16_f32 v171, v172, v173
	v_cvt_pk_bf16_f32 v172, v174, v175
	v_cvt_pk_bf16_f32 v173, v176, v177
	global_store_dwordx4 v[132:133], v[170:173], off nt
	v_lshl_add_u64 v[130:131], v[130:131], 0, s[6:7]
	global_load_dwordx4 v[154:157], v[136:137], off offset:2048
	global_load_dwordx4 v[158:161], v[136:137], off offset:2064
	global_load_dwordx4 v[162:165], v[136:137], off offset:2080
	global_load_dwordx4 v[166:169], v[136:137], off offset:2096
	s_waitcnt vmcnt(6)
	v_cndmask_b32_e64 v126, 1.0, v126, s[76:77]
	v_cndmask_b32_e64 v127, 1.0, v127, s[76:77]
	v_cndmask_b32_e64 v128, 1.0, v128, s[76:77]
	v_cndmask_b32_e64 v129, 1.0, v129, s[76:77]
	v_cndmask_b32_e64 v122, 1.0, v122, s[76:77]
	v_cndmask_b32_e64 v123, 1.0, v123, s[76:77]
	v_cndmask_b32_e64 v124, 1.0, v124, s[76:77]
	v_cndmask_b32_e64 v125, 1.0, v125, s[76:77]
	v_pk_mul_f32 v[94:95], v[152:153], v[94:95] op_sel_hi:[0,1]
	v_pk_mul_f32 v[96:97], v[152:153], v[96:97] op_sel_hi:[0,1]
	v_pk_mul_f32 v[90:91], v[152:153], v[90:91] op_sel_hi:[0,1]
	v_pk_mul_f32 v[92:93], v[152:153], v[92:93] op_sel_hi:[0,1]
	ds_bpermute_b32 v170, v0, v54
	ds_bpermute_b32 v171, v0, v55
	ds_bpermute_b32 v172, v0, v56
	ds_bpermute_b32 v173, v0, v57
	ds_bpermute_b32 v174, v0, v50
	ds_bpermute_b32 v175, v0, v51
	ds_bpermute_b32 v176, v0, v52
	ds_bpermute_b32 v177, v0, v53
	s_waitcnt lgkmcnt(0)
	v_pk_mul_f32 v[170:171], v[94:95], v[170:171]
	v_pk_mul_f32 v[172:173], v[96:97], v[172:173]
	v_pk_mul_f32 v[174:175], v[90:91], v[174:175]
	v_pk_mul_f32 v[176:177], v[92:93], v[176:177]
	v_pk_fma_f32 v[170:171], v[54:55], v[126:127], v[170:171]
	v_pk_fma_f32 v[172:173], v[56:57], v[128:129], v[172:173]
	v_pk_fma_f32 v[174:175], v[50:51], v[122:123], v[174:175]
	v_pk_fma_f32 v[176:177], v[52:53], v[124:125], v[176:177]
	v_pk_mul_f32 v[170:171], v[150:151], v[170:171] op_sel_hi:[0,1]
	v_pk_mul_f32 v[172:173], v[150:151], v[172:173] op_sel_hi:[0,1]
	v_pk_mul_f32 v[174:175], v[150:151], v[174:175] op_sel_hi:[0,1]
	v_pk_mul_f32 v[176:177], v[150:151], v[176:177] op_sel_hi:[0,1]
	v_cvt_pk_bf16_f32 v170, v170, v171
	v_cvt_pk_bf16_f32 v171, v172, v173
	v_cvt_pk_bf16_f32 v172, v174, v175
	v_cvt_pk_bf16_f32 v173, v176, v177
	global_store_dwordx4 v[130:131], v[170:173], off nt
	v_lshl_add_u64 v[132:133], v[130:131], 0, s[80:81]
	ds_bpermute_b32 v170, v0, v22
	ds_bpermute_b32 v171, v0, v23
	ds_bpermute_b32 v172, v0, v24
	ds_bpermute_b32 v173, v0, v25
	ds_bpermute_b32 v174, v0, v18
	ds_bpermute_b32 v175, v0, v19
	ds_bpermute_b32 v176, v0, v20
	ds_bpermute_b32 v177, v0, v21
	s_waitcnt lgkmcnt(0)
	v_pk_mul_f32 v[170:171], v[94:95], v[170:171]
	v_pk_mul_f32 v[172:173], v[96:97], v[172:173]
	v_pk_mul_f32 v[174:175], v[90:91], v[174:175]
	v_pk_mul_f32 v[176:177], v[92:93], v[176:177]
	v_pk_fma_f32 v[170:171], v[22:23], v[126:127], v[170:171]
	v_pk_fma_f32 v[172:173], v[24:25], v[128:129], v[172:173]
	v_pk_fma_f32 v[174:175], v[18:19], v[122:123], v[174:175]
	v_pk_fma_f32 v[176:177], v[20:21], v[124:125], v[176:177]
	v_pk_mul_f32 v[170:171], v[150:151], v[170:171] op_sel_hi:[0,1]
	v_pk_mul_f32 v[172:173], v[150:151], v[172:173] op_sel_hi:[0,1]
	v_pk_mul_f32 v[174:175], v[150:151], v[174:175] op_sel_hi:[0,1]
	v_pk_mul_f32 v[176:177], v[150:151], v[176:177] op_sel_hi:[0,1]
	v_cvt_pk_bf16_f32 v170, v170, v171
	v_cvt_pk_bf16_f32 v171, v172, v173
	v_cvt_pk_bf16_f32 v172, v174, v175
	v_cvt_pk_bf16_f32 v173, v176, v177
	global_store_dwordx4 v[132:133], v[170:173], off nt
	v_lshl_add_u64 v[130:131], v[130:131], 0, s[6:7]
	global_load_dwordx4 v[126:129], v[136:137], off offset:3072
	global_load_dwordx4 v[122:125], v[136:137], off offset:3088
	global_load_dwordx4 v[94:97], v[136:137], off offset:3104
	global_load_dwordx4 v[90:93], v[136:137], off offset:3120
	s_waitcnt vmcnt(6)
	v_cndmask_b32_e64 v154, 1.0, v154, s[76:77]
	v_cndmask_b32_e64 v155, 1.0, v155, s[76:77]
	v_cndmask_b32_e64 v156, 1.0, v156, s[76:77]
	v_cndmask_b32_e64 v157, 1.0, v157, s[76:77]
	v_cndmask_b32_e64 v158, 1.0, v158, s[76:77]
	v_cndmask_b32_e64 v159, 1.0, v159, s[76:77]
	v_cndmask_b32_e64 v160, 1.0, v160, s[76:77]
	v_cndmask_b32_e64 v161, 1.0, v161, s[76:77]
	v_pk_mul_f32 v[162:163], v[152:153], v[162:163] op_sel_hi:[0,1]
	v_pk_mul_f32 v[164:165], v[152:153], v[164:165] op_sel_hi:[0,1]
	v_pk_mul_f32 v[166:167], v[152:153], v[166:167] op_sel_hi:[0,1]
	v_pk_mul_f32 v[168:169], v[152:153], v[168:169] op_sel_hi:[0,1]
	ds_bpermute_b32 v170, v0, v46
	ds_bpermute_b32 v171, v0, v47
	ds_bpermute_b32 v172, v0, v48
	ds_bpermute_b32 v173, v0, v49
	ds_bpermute_b32 v174, v0, v42
	ds_bpermute_b32 v175, v0, v43
	ds_bpermute_b32 v176, v0, v44
	ds_bpermute_b32 v177, v0, v45
	s_waitcnt lgkmcnt(0)
	v_pk_mul_f32 v[170:171], v[162:163], v[170:171]
	v_pk_mul_f32 v[172:173], v[164:165], v[172:173]
	v_pk_mul_f32 v[174:175], v[166:167], v[174:175]
	v_pk_mul_f32 v[176:177], v[168:169], v[176:177]
	v_pk_fma_f32 v[170:171], v[46:47], v[154:155], v[170:171]
	v_pk_fma_f32 v[172:173], v[48:49], v[156:157], v[172:173]
	v_pk_fma_f32 v[174:175], v[42:43], v[158:159], v[174:175]
	v_pk_fma_f32 v[176:177], v[44:45], v[160:161], v[176:177]
	v_pk_mul_f32 v[170:171], v[150:151], v[170:171] op_sel_hi:[0,1]
	v_pk_mul_f32 v[172:173], v[150:151], v[172:173] op_sel_hi:[0,1]
	v_pk_mul_f32 v[174:175], v[150:151], v[174:175] op_sel_hi:[0,1]
	v_pk_mul_f32 v[176:177], v[150:151], v[176:177] op_sel_hi:[0,1]
	v_cvt_pk_bf16_f32 v170, v170, v171
	v_cvt_pk_bf16_f32 v171, v172, v173
	v_cvt_pk_bf16_f32 v172, v174, v175
	v_cvt_pk_bf16_f32 v173, v176, v177
	global_store_dwordx4 v[130:131], v[170:173], off nt
	v_lshl_add_u64 v[132:133], v[130:131], 0, s[80:81]
	ds_bpermute_b32 v170, v0, v14
	ds_bpermute_b32 v171, v0, v15
	ds_bpermute_b32 v172, v0, v16
	ds_bpermute_b32 v173, v0, v17
	ds_bpermute_b32 v174, v0, v10
	ds_bpermute_b32 v175, v0, v11
	ds_bpermute_b32 v176, v0, v12
	ds_bpermute_b32 v177, v0, v13
	s_waitcnt lgkmcnt(0)
	v_pk_mul_f32 v[170:171], v[162:163], v[170:171]
	v_pk_mul_f32 v[172:173], v[164:165], v[172:173]
	v_pk_mul_f32 v[174:175], v[166:167], v[174:175]
	v_pk_mul_f32 v[176:177], v[168:169], v[176:177]
	v_pk_fma_f32 v[170:171], v[14:15], v[154:155], v[170:171]
	v_pk_fma_f32 v[172:173], v[16:17], v[156:157], v[172:173]
	v_pk_fma_f32 v[174:175], v[10:11], v[158:159], v[174:175]
	v_pk_fma_f32 v[176:177], v[12:13], v[160:161], v[176:177]
	v_pk_mul_f32 v[170:171], v[150:151], v[170:171] op_sel_hi:[0,1]
	v_pk_mul_f32 v[172:173], v[150:151], v[172:173] op_sel_hi:[0,1]
	v_pk_mul_f32 v[174:175], v[150:151], v[174:175] op_sel_hi:[0,1]
	v_pk_mul_f32 v[176:177], v[150:151], v[176:177] op_sel_hi:[0,1]
	v_cvt_pk_bf16_f32 v170, v170, v171
	v_cvt_pk_bf16_f32 v171, v172, v173
	v_cvt_pk_bf16_f32 v172, v174, v175
	v_cvt_pk_bf16_f32 v173, v176, v177
	global_store_dwordx4 v[132:133], v[170:173], off nt
	v_lshl_add_u64 v[130:131], v[130:131], 0, s[6:7]
	s_waitcnt vmcnt(2)
	v_cndmask_b32_e64 v126, 1.0, v126, s[76:77]
	v_cndmask_b32_e64 v127, 1.0, v127, s[76:77]
	v_cndmask_b32_e64 v128, 1.0, v128, s[76:77]
	v_cndmask_b32_e64 v129, 1.0, v129, s[76:77]
	v_cndmask_b32_e64 v122, 1.0, v122, s[76:77]
	v_cndmask_b32_e64 v123, 1.0, v123, s[76:77]
	v_cndmask_b32_e64 v124, 1.0, v124, s[76:77]
	v_cndmask_b32_e64 v125, 1.0, v125, s[76:77]
	v_pk_mul_f32 v[94:95], v[152:153], v[94:95] op_sel_hi:[0,1]
	v_pk_mul_f32 v[96:97], v[152:153], v[96:97] op_sel_hi:[0,1]
	v_pk_mul_f32 v[90:91], v[152:153], v[90:91] op_sel_hi:[0,1]
	v_pk_mul_f32 v[92:93], v[152:153], v[92:93] op_sel_hi:[0,1]
	ds_bpermute_b32 v170, v0, v38
	ds_bpermute_b32 v171, v0, v39
	ds_bpermute_b32 v172, v0, v40
	ds_bpermute_b32 v173, v0, v41
	ds_bpermute_b32 v174, v0, v34
	ds_bpermute_b32 v175, v0, v35
	ds_bpermute_b32 v176, v0, v36
	ds_bpermute_b32 v177, v0, v37
	s_waitcnt lgkmcnt(0)
	v_pk_mul_f32 v[170:171], v[94:95], v[170:171]
	v_pk_mul_f32 v[172:173], v[96:97], v[172:173]
	v_pk_mul_f32 v[174:175], v[90:91], v[174:175]
	v_pk_mul_f32 v[176:177], v[92:93], v[176:177]
	v_pk_fma_f32 v[170:171], v[38:39], v[126:127], v[170:171]
	v_pk_fma_f32 v[172:173], v[40:41], v[128:129], v[172:173]
	v_pk_fma_f32 v[174:175], v[34:35], v[122:123], v[174:175]
	v_pk_fma_f32 v[176:177], v[36:37], v[124:125], v[176:177]
	v_pk_mul_f32 v[170:171], v[150:151], v[170:171] op_sel_hi:[0,1]
	v_pk_mul_f32 v[172:173], v[150:151], v[172:173] op_sel_hi:[0,1]
	v_pk_mul_f32 v[174:175], v[150:151], v[174:175] op_sel_hi:[0,1]
	v_pk_mul_f32 v[176:177], v[150:151], v[176:177] op_sel_hi:[0,1]
	v_cvt_pk_bf16_f32 v170, v170, v171
	v_cvt_pk_bf16_f32 v171, v172, v173
	v_cvt_pk_bf16_f32 v172, v174, v175
	v_cvt_pk_bf16_f32 v173, v176, v177
	global_store_dwordx4 v[130:131], v[170:173], off nt
	v_lshl_add_u64 v[132:133], v[130:131], 0, s[80:81]
	ds_bpermute_b32 v170, v0, v6
	ds_bpermute_b32 v171, v0, v7
	ds_bpermute_b32 v172, v0, v8
	ds_bpermute_b32 v173, v0, v9
	ds_bpermute_b32 v174, v0, v2
	ds_bpermute_b32 v175, v0, v3
	ds_bpermute_b32 v176, v0, v4
	ds_bpermute_b32 v177, v0, v5
	s_waitcnt lgkmcnt(0)
	v_pk_mul_f32 v[170:171], v[94:95], v[170:171]
	v_pk_mul_f32 v[172:173], v[96:97], v[172:173]
	v_pk_mul_f32 v[174:175], v[90:91], v[174:175]
	v_pk_mul_f32 v[176:177], v[92:93], v[176:177]
	v_pk_fma_f32 v[170:171], v[6:7], v[126:127], v[170:171]
	v_pk_fma_f32 v[172:173], v[8:9], v[128:129], v[172:173]
	v_pk_fma_f32 v[174:175], v[2:3], v[122:123], v[174:175]
	v_pk_fma_f32 v[176:177], v[4:5], v[124:125], v[176:177]
	v_pk_mul_f32 v[170:171], v[150:151], v[170:171] op_sel_hi:[0,1]
	v_pk_mul_f32 v[172:173], v[150:151], v[172:173] op_sel_hi:[0,1]
	v_pk_mul_f32 v[174:175], v[150:151], v[174:175] op_sel_hi:[0,1]
	v_pk_mul_f32 v[176:177], v[150:151], v[176:177] op_sel_hi:[0,1]
	v_cvt_pk_bf16_f32 v170, v170, v171
	v_cvt_pk_bf16_f32 v171, v172, v173
	v_cvt_pk_bf16_f32 v172, v174, v175
	v_cvt_pk_bf16_f32 v173, v176, v177
	global_store_dwordx4 v[132:133], v[170:173], off nt
	s_branch .Lqk_done
.Lqk_nonrot:
	v_pk_mul_f32 v[170:171], v[150:151], v[126:127] op_sel_hi:[0,1]
	v_pk_mul_f32 v[172:173], v[150:151], v[128:129] op_sel_hi:[0,1]
	v_pk_mul_f32 v[174:175], v[150:151], v[122:123] op_sel_hi:[0,1]
	v_pk_mul_f32 v[176:177], v[150:151], v[124:125] op_sel_hi:[0,1]
	v_cvt_pk_bf16_f32 v170, v170, v171
	v_cvt_pk_bf16_f32 v171, v172, v173
	v_cvt_pk_bf16_f32 v172, v174, v175
	v_cvt_pk_bf16_f32 v173, v176, v177
	global_store_dwordx4 v[130:131], v[170:173], off nt
	v_lshl_add_u64 v[132:133], v[130:131], 0, s[80:81]
	s_nop 0
	v_pk_mul_f32 v[170:171], v[150:151], v[94:95] op_sel_hi:[0,1]
	v_pk_mul_f32 v[172:173], v[150:151], v[96:97] op_sel_hi:[0,1]
	v_pk_mul_f32 v[174:175], v[150:151], v[90:91] op_sel_hi:[0,1]
	v_pk_mul_f32 v[176:177], v[150:151], v[92:93] op_sel_hi:[0,1]
	v_cvt_pk_bf16_f32 v170, v170, v171
	v_cvt_pk_bf16_f32 v171, v172, v173
	v_cvt_pk_bf16_f32 v172, v174, v175
	v_cvt_pk_bf16_f32 v173, v176, v177
	global_store_dwordx4 v[132:133], v[170:173], off nt
	v_lshl_add_u64 v[130:131], v[130:131], 0, s[6:7]
	s_nop 0
	v_pk_mul_f32 v[170:171], v[150:151], v[118:119] op_sel_hi:[0,1]
	v_pk_mul_f32 v[172:173], v[150:151], v[120:121] op_sel_hi:[0,1]
	v_pk_mul_f32 v[174:175], v[150:151], v[114:115] op_sel_hi:[0,1]
	v_pk_mul_f32 v[176:177], v[150:151], v[116:117] op_sel_hi:[0,1]
	v_cvt_pk_bf16_f32 v170, v170, v171
	v_cvt_pk_bf16_f32 v171, v172, v173
	v_cvt_pk_bf16_f32 v172, v174, v175
	v_cvt_pk_bf16_f32 v173, v176, v177
	global_store_dwordx4 v[130:131], v[170:173], off nt
	v_lshl_add_u64 v[132:133], v[130:131], 0, s[80:81]
	s_nop 0
	v_pk_mul_f32 v[170:171], v[150:151], v[86:87] op_sel_hi:[0,1]
	v_pk_mul_f32 v[172:173], v[150:151], v[88:89] op_sel_hi:[0,1]
	v_pk_mul_f32 v[174:175], v[150:151], v[82:83] op_sel_hi:[0,1]
	v_pk_mul_f32 v[176:177], v[150:151], v[84:85] op_sel_hi:[0,1]
	v_cvt_pk_bf16_f32 v170, v170, v171
	v_cvt_pk_bf16_f32 v171, v172, v173
	v_cvt_pk_bf16_f32 v172, v174, v175
	v_cvt_pk_bf16_f32 v173, v176, v177
	global_store_dwordx4 v[132:133], v[170:173], off nt
	v_lshl_add_u64 v[130:131], v[130:131], 0, s[6:7]
	s_nop 0
	v_pk_mul_f32 v[170:171], v[150:151], v[110:111] op_sel_hi:[0,1]
	v_pk_mul_f32 v[172:173], v[150:151], v[112:113] op_sel_hi:[0,1]
	v_pk_mul_f32 v[174:175], v[150:151], v[106:107] op_sel_hi:[0,1]
	v_pk_mul_f32 v[176:177], v[150:151], v[108:109] op_sel_hi:[0,1]
	v_cvt_pk_bf16_f32 v170, v170, v171
	v_cvt_pk_bf16_f32 v171, v172, v173
	v_cvt_pk_bf16_f32 v172, v174, v175
	v_cvt_pk_bf16_f32 v173, v176, v177
	global_store_dwordx4 v[130:131], v[170:173], off nt
	v_lshl_add_u64 v[132:133], v[130:131], 0, s[80:81]
	s_nop 0
	v_pk_mul_f32 v[170:171], v[150:151], v[78:79] op_sel_hi:[0,1]
	v_pk_mul_f32 v[172:173], v[150:151], v[80:81] op_sel_hi:[0,1]
	v_pk_mul_f32 v[174:175], v[150:151], v[74:75] op_sel_hi:[0,1]
	v_pk_mul_f32 v[176:177], v[150:151], v[76:77] op_sel_hi:[0,1]
	v_cvt_pk_bf16_f32 v170, v170, v171
	v_cvt_pk_bf16_f32 v171, v172, v173
	v_cvt_pk_bf16_f32 v172, v174, v175
	v_cvt_pk_bf16_f32 v173, v176, v177
	global_store_dwordx4 v[132:133], v[170:173], off nt
	v_lshl_add_u64 v[130:131], v[130:131], 0, s[6:7]
	s_nop 0
	v_pk_mul_f32 v[170:171], v[150:151], v[102:103] op_sel_hi:[0,1]
	v_pk_mul_f32 v[172:173], v[150:151], v[104:105] op_sel_hi:[0,1]
	v_pk_mul_f32 v[174:175], v[150:151], v[98:99] op_sel_hi:[0,1]
	v_pk_mul_f32 v[176:177], v[150:151], v[100:101] op_sel_hi:[0,1]
	v_cvt_pk_bf16_f32 v170, v170, v171
	v_cvt_pk_bf16_f32 v171, v172, v173
	v_cvt_pk_bf16_f32 v172, v174, v175
	v_cvt_pk_bf16_f32 v173, v176, v177
	global_store_dwordx4 v[130:131], v[170:173], off nt
	v_lshl_add_u64 v[132:133], v[130:131], 0, s[80:81]
	s_nop 0
	v_pk_mul_f32 v[170:171], v[150:151], v[70:71] op_sel_hi:[0,1]
	v_pk_mul_f32 v[172:173], v[150:151], v[72:73] op_sel_hi:[0,1]
	v_pk_mul_f32 v[174:175], v[150:151], v[66:67] op_sel_hi:[0,1]
	v_pk_mul_f32 v[176:177], v[150:151], v[68:69] op_sel_hi:[0,1]
	v_cvt_pk_bf16_f32 v170, v170, v171
	v_cvt_pk_bf16_f32 v171, v172, v173
	v_cvt_pk_bf16_f32 v172, v174, v175
	v_cvt_pk_bf16_f32 v173, v176, v177
	global_store_dwordx4 v[132:133], v[170:173], off nt
	v_lshl_add_u64 v[130:131], v[130:131], 0, s[0:1]
	s_nop 0
	v_pk_mul_f32 v[170:171], v[150:151], v[62:63] op_sel_hi:[0,1]
	v_pk_mul_f32 v[172:173], v[150:151], v[64:65] op_sel_hi:[0,1]
	v_pk_mul_f32 v[174:175], v[150:151], v[58:59] op_sel_hi:[0,1]
	v_pk_mul_f32 v[176:177], v[150:151], v[60:61] op_sel_hi:[0,1]
	v_cvt_pk_bf16_f32 v170, v170, v171
	v_cvt_pk_bf16_f32 v171, v172, v173
	v_cvt_pk_bf16_f32 v172, v174, v175
	v_cvt_pk_bf16_f32 v173, v176, v177
	global_store_dwordx4 v[130:131], v[170:173], off nt
	v_lshl_add_u64 v[132:133], v[130:131], 0, s[80:81]
	s_nop 0
	v_pk_mul_f32 v[170:171], v[150:151], v[30:31] op_sel_hi:[0,1]
	v_pk_mul_f32 v[172:173], v[150:151], v[32:33] op_sel_hi:[0,1]
	v_pk_mul_f32 v[174:175], v[150:151], v[26:27] op_sel_hi:[0,1]
	v_pk_mul_f32 v[176:177], v[150:151], v[28:29] op_sel_hi:[0,1]
	v_cvt_pk_bf16_f32 v170, v170, v171
	v_cvt_pk_bf16_f32 v171, v172, v173
	v_cvt_pk_bf16_f32 v172, v174, v175
	v_cvt_pk_bf16_f32 v173, v176, v177
	global_store_dwordx4 v[132:133], v[170:173], off nt
	v_lshl_add_u64 v[130:131], v[130:131], 0, s[6:7]
	s_nop 0
	v_pk_mul_f32 v[170:171], v[150:151], v[54:55] op_sel_hi:[0,1]
	v_pk_mul_f32 v[172:173], v[150:151], v[56:57] op_sel_hi:[0,1]
	v_pk_mul_f32 v[174:175], v[150:151], v[50:51] op_sel_hi:[0,1]
	v_pk_mul_f32 v[176:177], v[150:151], v[52:53] op_sel_hi:[0,1]
	v_cvt_pk_bf16_f32 v170, v170, v171
	v_cvt_pk_bf16_f32 v171, v172, v173
	v_cvt_pk_bf16_f32 v172, v174, v175
	v_cvt_pk_bf16_f32 v173, v176, v177
	global_store_dwordx4 v[130:131], v[170:173], off nt
	v_lshl_add_u64 v[132:133], v[130:131], 0, s[80:81]
	s_nop 0
	v_pk_mul_f32 v[170:171], v[150:151], v[22:23] op_sel_hi:[0,1]
	v_pk_mul_f32 v[172:173], v[150:151], v[24:25] op_sel_hi:[0,1]
	v_pk_mul_f32 v[174:175], v[150:151], v[18:19] op_sel_hi:[0,1]
	v_pk_mul_f32 v[176:177], v[150:151], v[20:21] op_sel_hi:[0,1]
	v_cvt_pk_bf16_f32 v170, v170, v171
	v_cvt_pk_bf16_f32 v171, v172, v173
	v_cvt_pk_bf16_f32 v172, v174, v175
	v_cvt_pk_bf16_f32 v173, v176, v177
	global_store_dwordx4 v[132:133], v[170:173], off nt
	v_lshl_add_u64 v[130:131], v[130:131], 0, s[6:7]
	s_nop 0
	v_pk_mul_f32 v[170:171], v[150:151], v[46:47] op_sel_hi:[0,1]
	v_pk_mul_f32 v[172:173], v[150:151], v[48:49] op_sel_hi:[0,1]
	v_pk_mul_f32 v[174:175], v[150:151], v[42:43] op_sel_hi:[0,1]
	v_pk_mul_f32 v[176:177], v[150:151], v[44:45] op_sel_hi:[0,1]
	v_cvt_pk_bf16_f32 v170, v170, v171
	v_cvt_pk_bf16_f32 v171, v172, v173
	v_cvt_pk_bf16_f32 v172, v174, v175
	v_cvt_pk_bf16_f32 v173, v176, v177
	global_store_dwordx4 v[130:131], v[170:173], off nt
	v_lshl_add_u64 v[132:133], v[130:131], 0, s[80:81]
	s_nop 0
	v_pk_mul_f32 v[170:171], v[150:151], v[14:15] op_sel_hi:[0,1]
	v_pk_mul_f32 v[172:173], v[150:151], v[16:17] op_sel_hi:[0,1]
	v_pk_mul_f32 v[174:175], v[150:151], v[10:11] op_sel_hi:[0,1]
	v_pk_mul_f32 v[176:177], v[150:151], v[12:13] op_sel_hi:[0,1]
	v_cvt_pk_bf16_f32 v170, v170, v171
	v_cvt_pk_bf16_f32 v171, v172, v173
	v_cvt_pk_bf16_f32 v172, v174, v175
	v_cvt_pk_bf16_f32 v173, v176, v177
	global_store_dwordx4 v[132:133], v[170:173], off nt
	v_lshl_add_u64 v[130:131], v[130:131], 0, s[6:7]
	s_nop 0
	v_pk_mul_f32 v[170:171], v[150:151], v[38:39] op_sel_hi:[0,1]
	v_pk_mul_f32 v[172:173], v[150:151], v[40:41] op_sel_hi:[0,1]
	v_pk_mul_f32 v[174:175], v[150:151], v[34:35] op_sel_hi:[0,1]
	v_pk_mul_f32 v[176:177], v[150:151], v[36:37] op_sel_hi:[0,1]
	v_cvt_pk_bf16_f32 v170, v170, v171
	v_cvt_pk_bf16_f32 v171, v172, v173
	v_cvt_pk_bf16_f32 v172, v174, v175
	v_cvt_pk_bf16_f32 v173, v176, v177
	global_store_dwordx4 v[130:131], v[170:173], off nt
	v_lshl_add_u64 v[132:133], v[130:131], 0, s[80:81]
	s_nop 0
	v_pk_mul_f32 v[170:171], v[150:151], v[6:7] op_sel_hi:[0,1]
	v_pk_mul_f32 v[172:173], v[150:151], v[8:9] op_sel_hi:[0,1]
	v_pk_mul_f32 v[174:175], v[150:151], v[2:3] op_sel_hi:[0,1]
	v_pk_mul_f32 v[176:177], v[150:151], v[4:5] op_sel_hi:[0,1]
	v_cvt_pk_bf16_f32 v170, v170, v171
	v_cvt_pk_bf16_f32 v171, v172, v173
	v_cvt_pk_bf16_f32 v172, v174, v175
	v_cvt_pk_bf16_f32 v173, v176, v177
	global_store_dwordx4 v[132:133], v[170:173], off nt
	s_nop 0

.LBB0_1113:
	s_andn2_b64 vcc, exec, s[0:1]
	s_cbranch_vccnz .LBB0_1118
	s_cmp_gt_i32 s2, 1
	s_mov_b64 s[0:1], -1
	s_cbranch_scc0 .LBB0_1116
	v_lshlrev_b32_e32 v0, 3, v183
	v_lshl_add_u32 v130, v182, 7, v0
	s_mul_i32 s0, s70, 12
	s_add_i32 s0, s0, s69
	s_ashr_i32 s1, s0, 31
	s_lshl_b64 s[0:1], s[0:1], 17
	s_add_u32 s0, s34, s0
	s_addc_u32 s1, s35, s1
	s_add_u32 s0, s0, s24
	s_addc_u32 s1, s1, s25
	v_ashrrev_i32_e32 v131, 31, v130
	v_lshl_add_u64 v[130:131], v[130:131], 1, s[0:1]
	s_mov_b32 s0, 0xbfb8aa3b
	s_mov_b32 s1, 1.0
	s_mov_b32 s6, 0x2000
	s_mov_b32 s7, 0
	v_pk_mul_f32 v[148:149], v[126:127], s[0:1] op_sel_hi:[1,0]
	v_pk_mul_f32 v[150:151], v[128:129], s[0:1] op_sel_hi:[1,0]
	v_pk_mul_f32 v[152:153], v[122:123], s[0:1] op_sel_hi:[1,0]
	v_pk_mul_f32 v[154:155], v[124:125], s[0:1] op_sel_hi:[1,0]
	v_exp_f32_e32 v148, v148
	v_exp_f32_e32 v149, v149
	v_exp_f32_e32 v150, v150
	v_exp_f32_e32 v151, v151
	v_exp_f32_e32 v152, v152
	v_exp_f32_e32 v153, v153
	v_exp_f32_e32 v154, v154
	v_exp_f32_e32 v155, v155
	v_pk_add_f32 v[148:149], v[148:149], s[0:1] op_sel:[0,1] op_sel_hi:[1,1]
	v_pk_add_f32 v[150:151], v[150:151], s[0:1] op_sel:[0,1] op_sel_hi:[1,1]
	v_pk_add_f32 v[152:153], v[152:153], s[0:1] op_sel:[0,1] op_sel_hi:[1,1]
	v_pk_add_f32 v[154:155], v[154:155], s[0:1] op_sel:[0,1] op_sel_hi:[1,1]
	v_rcp_f32_e32 v148, v148
	v_rcp_f32_e32 v149, v149
	v_rcp_f32_e32 v150, v150
	v_rcp_f32_e32 v151, v151
	v_rcp_f32_e32 v152, v152
	v_rcp_f32_e32 v153, v153
	v_rcp_f32_e32 v154, v154
	v_rcp_f32_e32 v155, v155
	v_max_f32_e32 v148, 0x1e3ce508, v148
	v_max_f32_e32 v149, 0x1e3ce508, v149
	v_max_f32_e32 v150, 0x1e3ce508, v150
	v_max_f32_e32 v151, 0x1e3ce508, v151
	v_max_f32_e32 v152, 0x1e3ce508, v152
	v_max_f32_e32 v153, 0x1e3ce508, v153
	v_max_f32_e32 v154, 0x1e3ce508, v154
	v_max_f32_e32 v155, 0x1e3ce508, v155
	v_cvt_pk_bf16_f32 v132, v148, v149
	v_cvt_pk_bf16_f32 v133, v150, v151
	v_cvt_pk_bf16_f32 v134, v152, v153
	v_cvt_pk_bf16_f32 v135, v154, v155
	flat_store_dwordx4 v[130:131], v[132:135] nt
	v_lshl_add_u64 v[130:131], v[130:131], 0, s[6:7]
	v_pk_mul_f32 v[148:149], v[94:95], s[0:1] op_sel_hi:[1,0]
	v_pk_mul_f32 v[150:151], v[96:97], s[0:1] op_sel_hi:[1,0]
	v_pk_mul_f32 v[152:153], v[90:91], s[0:1] op_sel_hi:[1,0]
	v_pk_mul_f32 v[154:155], v[92:93], s[0:1] op_sel_hi:[1,0]
	v_exp_f32_e32 v148, v148
	v_exp_f32_e32 v149, v149
	v_exp_f32_e32 v150, v150
	v_exp_f32_e32 v151, v151
	v_exp_f32_e32 v152, v152
	v_exp_f32_e32 v153, v153
	v_exp_f32_e32 v154, v154
	v_exp_f32_e32 v155, v155
	v_pk_add_f32 v[148:149], v[148:149], s[0:1] op_sel:[0,1] op_sel_hi:[1,1]
	v_pk_add_f32 v[150:151], v[150:151], s[0:1] op_sel:[0,1] op_sel_hi:[1,1]
	v_pk_add_f32 v[152:153], v[152:153], s[0:1] op_sel:[0,1] op_sel_hi:[1,1]
	v_pk_add_f32 v[154:155], v[154:155], s[0:1] op_sel:[0,1] op_sel_hi:[1,1]
	v_rcp_f32_e32 v148, v148
	v_rcp_f32_e32 v149, v149
	v_rcp_f32_e32 v150, v150
	v_rcp_f32_e32 v151, v151
	v_rcp_f32_e32 v152, v152
	v_rcp_f32_e32 v153, v153
	v_rcp_f32_e32 v154, v154
	v_rcp_f32_e32 v155, v155
	v_max_f32_e32 v148, 0x1e3ce508, v148
	v_max_f32_e32 v149, 0x1e3ce508, v149
	v_max_f32_e32 v150, 0x1e3ce508, v150
	v_max_f32_e32 v151, 0x1e3ce508, v151
	v_max_f32_e32 v152, 0x1e3ce508, v152
	v_max_f32_e32 v153, 0x1e3ce508, v153
	v_max_f32_e32 v154, 0x1e3ce508, v154
	v_max_f32_e32 v155, 0x1e3ce508, v155
	v_cvt_pk_bf16_f32 v132, v148, v149
	v_cvt_pk_bf16_f32 v133, v150, v151
	v_cvt_pk_bf16_f32 v134, v152, v153
	v_cvt_pk_bf16_f32 v135, v154, v155
	flat_store_dwordx4 v[130:131], v[132:135] nt
	v_lshl_add_u64 v[130:131], v[130:131], 0, s[6:7]
	v_pk_mul_f32 v[148:149], v[118:119], s[0:1] op_sel_hi:[1,0]
	v_pk_mul_f32 v[150:151], v[120:121], s[0:1] op_sel_hi:[1,0]
	v_pk_mul_f32 v[152:153], v[114:115], s[0:1] op_sel_hi:[1,0]
	v_pk_mul_f32 v[154:155], v[116:117], s[0:1] op_sel_hi:[1,0]
	v_exp_f32_e32 v148, v148
	v_exp_f32_e32 v149, v149
	v_exp_f32_e32 v150, v150
	v_exp_f32_e32 v151, v151
	v_exp_f32_e32 v152, v152
	v_exp_f32_e32 v153, v153
	v_exp_f32_e32 v154, v154
	v_exp_f32_e32 v155, v155
	v_pk_add_f32 v[148:149], v[148:149], s[0:1] op_sel:[0,1] op_sel_hi:[1,1]
	v_pk_add_f32 v[150:151], v[150:151], s[0:1] op_sel:[0,1] op_sel_hi:[1,1]
	v_pk_add_f32 v[152:153], v[152:153], s[0:1] op_sel:[0,1] op_sel_hi:[1,1]
	v_pk_add_f32 v[154:155], v[154:155], s[0:1] op_sel:[0,1] op_sel_hi:[1,1]
	v_rcp_f32_e32 v148, v148
	v_rcp_f32_e32 v149, v149
	v_rcp_f32_e32 v150, v150
	v_rcp_f32_e32 v151, v151
	v_rcp_f32_e32 v152, v152
	v_rcp_f32_e32 v153, v153
	v_rcp_f32_e32 v154, v154
	v_rcp_f32_e32 v155, v155
	v_max_f32_e32 v148, 0x1e3ce508, v148
	v_max_f32_e32 v149, 0x1e3ce508, v149
	v_max_f32_e32 v150, 0x1e3ce508, v150
	v_max_f32_e32 v151, 0x1e3ce508, v151
	v_max_f32_e32 v152, 0x1e3ce508, v152
	v_max_f32_e32 v153, 0x1e3ce508, v153
	v_max_f32_e32 v154, 0x1e3ce508, v154
	v_max_f32_e32 v155, 0x1e3ce508, v155
	v_cvt_pk_bf16_f32 v132, v148, v149
	v_cvt_pk_bf16_f32 v133, v150, v151
	v_cvt_pk_bf16_f32 v134, v152, v153
	v_cvt_pk_bf16_f32 v135, v154, v155
	flat_store_dwordx4 v[130:131], v[132:135] nt
	v_lshl_add_u64 v[130:131], v[130:131], 0, s[6:7]
	v_pk_mul_f32 v[148:149], v[86:87], s[0:1] op_sel_hi:[1,0]
	v_pk_mul_f32 v[150:151], v[88:89], s[0:1] op_sel_hi:[1,0]
	v_pk_mul_f32 v[152:153], v[82:83], s[0:1] op_sel_hi:[1,0]
	v_pk_mul_f32 v[154:155], v[84:85], s[0:1] op_sel_hi:[1,0]
	v_exp_f32_e32 v148, v148
	v_exp_f32_e32 v149, v149
	v_exp_f32_e32 v150, v150
	v_exp_f32_e32 v151, v151
	v_exp_f32_e32 v152, v152
	v_exp_f32_e32 v153, v153
	v_exp_f32_e32 v154, v154
	v_exp_f32_e32 v155, v155
	v_pk_add_f32 v[148:149], v[148:149], s[0:1] op_sel:[0,1] op_sel_hi:[1,1]
	v_pk_add_f32 v[150:151], v[150:151], s[0:1] op_sel:[0,1] op_sel_hi:[1,1]
	v_pk_add_f32 v[152:153], v[152:153], s[0:1] op_sel:[0,1] op_sel_hi:[1,1]
	v_pk_add_f32 v[154:155], v[154:155], s[0:1] op_sel:[0,1] op_sel_hi:[1,1]
	v_rcp_f32_e32 v148, v148
	v_rcp_f32_e32 v149, v149
	v_rcp_f32_e32 v150, v150
	v_rcp_f32_e32 v151, v151
	v_rcp_f32_e32 v152, v152
	v_rcp_f32_e32 v153, v153
	v_rcp_f32_e32 v154, v154
	v_rcp_f32_e32 v155, v155
	v_max_f32_e32 v148, 0x1e3ce508, v148
	v_max_f32_e32 v149, 0x1e3ce508, v149
	v_max_f32_e32 v150, 0x1e3ce508, v150
	v_max_f32_e32 v151, 0x1e3ce508, v151
	v_max_f32_e32 v152, 0x1e3ce508, v152
	v_max_f32_e32 v153, 0x1e3ce508, v153
	v_max_f32_e32 v154, 0x1e3ce508, v154
	v_max_f32_e32 v155, 0x1e3ce508, v155
	v_cvt_pk_bf16_f32 v132, v148, v149
	v_cvt_pk_bf16_f32 v133, v150, v151
	v_cvt_pk_bf16_f32 v134, v152, v153
	v_cvt_pk_bf16_f32 v135, v154, v155
	flat_store_dwordx4 v[130:131], v[132:135] nt
	v_lshl_add_u64 v[130:131], v[130:131], 0, s[6:7]
	v_pk_mul_f32 v[148:149], v[110:111], s[0:1] op_sel_hi:[1,0]
	v_pk_mul_f32 v[150:151], v[112:113], s[0:1] op_sel_hi:[1,0]
	v_pk_mul_f32 v[152:153], v[106:107], s[0:1] op_sel_hi:[1,0]
	v_pk_mul_f32 v[154:155], v[108:109], s[0:1] op_sel_hi:[1,0]
	v_exp_f32_e32 v148, v148
	v_exp_f32_e32 v149, v149
	v_exp_f32_e32 v150, v150
	v_exp_f32_e32 v151, v151
	v_exp_f32_e32 v152, v152
	v_exp_f32_e32 v153, v153
	v_exp_f32_e32 v154, v154
	v_exp_f32_e32 v155, v155
	v_pk_add_f32 v[148:149], v[148:149], s[0:1] op_sel:[0,1] op_sel_hi:[1,1]
	v_pk_add_f32 v[150:151], v[150:151], s[0:1] op_sel:[0,1] op_sel_hi:[1,1]
	v_pk_add_f32 v[152:153], v[152:153], s[0:1] op_sel:[0,1] op_sel_hi:[1,1]
	v_pk_add_f32 v[154:155], v[154:155], s[0:1] op_sel:[0,1] op_sel_hi:[1,1]
	v_rcp_f32_e32 v148, v148
	v_rcp_f32_e32 v149, v149
	v_rcp_f32_e32 v150, v150
	v_rcp_f32_e32 v151, v151
	v_rcp_f32_e32 v152, v152
	v_rcp_f32_e32 v153, v153
	v_rcp_f32_e32 v154, v154
	v_rcp_f32_e32 v155, v155
	v_max_f32_e32 v148, 0x1e3ce508, v148
	v_max_f32_e32 v149, 0x1e3ce508, v149
	v_max_f32_e32 v150, 0x1e3ce508, v150
	v_max_f32_e32 v151, 0x1e3ce508, v151
	v_max_f32_e32 v152, 0x1e3ce508, v152
	v_max_f32_e32 v153, 0x1e3ce508, v153
	v_max_f32_e32 v154, 0x1e3ce508, v154
	v_max_f32_e32 v155, 0x1e3ce508, v155
	v_cvt_pk_bf16_f32 v132, v148, v149
	v_cvt_pk_bf16_f32 v133, v150, v151
	v_cvt_pk_bf16_f32 v134, v152, v153
	v_cvt_pk_bf16_f32 v135, v154, v155
	flat_store_dwordx4 v[130:131], v[132:135] nt
	v_lshl_add_u64 v[130:131], v[130:131], 0, s[6:7]
	v_pk_mul_f32 v[148:149], v[78:79], s[0:1] op_sel_hi:[1,0]
	v_pk_mul_f32 v[150:151], v[80:81], s[0:1] op_sel_hi:[1,0]
	v_pk_mul_f32 v[152:153], v[74:75], s[0:1] op_sel_hi:[1,0]
	v_pk_mul_f32 v[154:155], v[76:77], s[0:1] op_sel_hi:[1,0]
	v_exp_f32_e32 v148, v148
	v_exp_f32_e32 v149, v149
	v_exp_f32_e32 v150, v150
	v_exp_f32_e32 v151, v151
	v_exp_f32_e32 v152, v152
	v_exp_f32_e32 v153, v153
	v_exp_f32_e32 v154, v154
	v_exp_f32_e32 v155, v155
	v_pk_add_f32 v[148:149], v[148:149], s[0:1] op_sel:[0,1] op_sel_hi:[1,1]
	v_pk_add_f32 v[150:151], v[150:151], s[0:1] op_sel:[0,1] op_sel_hi:[1,1]
	v_pk_add_f32 v[152:153], v[152:153], s[0:1] op_sel:[0,1] op_sel_hi:[1,1]
	v_pk_add_f32 v[154:155], v[154:155], s[0:1] op_sel:[0,1] op_sel_hi:[1,1]
	v_rcp_f32_e32 v148, v148
	v_rcp_f32_e32 v149, v149
	v_rcp_f32_e32 v150, v150
	v_rcp_f32_e32 v151, v151
	v_rcp_f32_e32 v152, v152
	v_rcp_f32_e32 v153, v153
	v_rcp_f32_e32 v154, v154
	v_rcp_f32_e32 v155, v155
	v_max_f32_e32 v148, 0x1e3ce508, v148
	v_max_f32_e32 v149, 0x1e3ce508, v149
	v_max_f32_e32 v150, 0x1e3ce508, v150
	v_max_f32_e32 v151, 0x1e3ce508, v151
	v_max_f32_e32 v152, 0x1e3ce508, v152
	v_max_f32_e32 v153, 0x1e3ce508, v153
	v_max_f32_e32 v154, 0x1e3ce508, v154
	v_max_f32_e32 v155, 0x1e3ce508, v155
	v_cvt_pk_bf16_f32 v132, v148, v149
	v_cvt_pk_bf16_f32 v133, v150, v151
	v_cvt_pk_bf16_f32 v134, v152, v153
	v_cvt_pk_bf16_f32 v135, v154, v155
	flat_store_dwordx4 v[130:131], v[132:135] nt
	v_lshl_add_u64 v[130:131], v[130:131], 0, s[6:7]
	v_pk_mul_f32 v[148:149], v[102:103], s[0:1] op_sel_hi:[1,0]
	v_pk_mul_f32 v[150:151], v[104:105], s[0:1] op_sel_hi:[1,0]
	v_pk_mul_f32 v[152:153], v[98:99], s[0:1] op_sel_hi:[1,0]
	v_pk_mul_f32 v[154:155], v[100:101], s[0:1] op_sel_hi:[1,0]
	v_exp_f32_e32 v148, v148
	v_exp_f32_e32 v149, v149
	v_exp_f32_e32 v150, v150
	v_exp_f32_e32 v151, v151
	v_exp_f32_e32 v152, v152
	v_exp_f32_e32 v153, v153
	v_exp_f32_e32 v154, v154
	v_exp_f32_e32 v155, v155
	v_pk_add_f32 v[148:149], v[148:149], s[0:1] op_sel:[0,1] op_sel_hi:[1,1]
	v_pk_add_f32 v[150:151], v[150:151], s[0:1] op_sel:[0,1] op_sel_hi:[1,1]
	v_pk_add_f32 v[152:153], v[152:153], s[0:1] op_sel:[0,1] op_sel_hi:[1,1]
	v_pk_add_f32 v[154:155], v[154:155], s[0:1] op_sel:[0,1] op_sel_hi:[1,1]
	v_rcp_f32_e32 v148, v148
	v_rcp_f32_e32 v149, v149
	v_rcp_f32_e32 v150, v150
	v_rcp_f32_e32 v151, v151
	v_rcp_f32_e32 v152, v152
	v_rcp_f32_e32 v153, v153
	v_rcp_f32_e32 v154, v154
	v_rcp_f32_e32 v155, v155
	v_max_f32_e32 v148, 0x1e3ce508, v148
	v_max_f32_e32 v149, 0x1e3ce508, v149
	v_max_f32_e32 v150, 0x1e3ce508, v150
	v_max_f32_e32 v151, 0x1e3ce508, v151
	v_max_f32_e32 v152, 0x1e3ce508, v152
	v_max_f32_e32 v153, 0x1e3ce508, v153
	v_max_f32_e32 v154, 0x1e3ce508, v154
	v_max_f32_e32 v155, 0x1e3ce508, v155
	v_cvt_pk_bf16_f32 v132, v148, v149
	v_cvt_pk_bf16_f32 v133, v150, v151
	v_cvt_pk_bf16_f32 v134, v152, v153
	v_cvt_pk_bf16_f32 v135, v154, v155
	flat_store_dwordx4 v[130:131], v[132:135] nt
	v_lshl_add_u64 v[130:131], v[130:131], 0, s[6:7]
	v_pk_mul_f32 v[148:149], v[70:71], s[0:1] op_sel_hi:[1,0]
	v_pk_mul_f32 v[150:151], v[72:73], s[0:1] op_sel_hi:[1,0]
	v_pk_mul_f32 v[152:153], v[66:67], s[0:1] op_sel_hi:[1,0]
	v_pk_mul_f32 v[154:155], v[68:69], s[0:1] op_sel_hi:[1,0]
	v_exp_f32_e32 v148, v148
	v_exp_f32_e32 v149, v149
	v_exp_f32_e32 v150, v150
	v_exp_f32_e32 v151, v151
	v_exp_f32_e32 v152, v152
	v_exp_f32_e32 v153, v153
	v_exp_f32_e32 v154, v154
	v_exp_f32_e32 v155, v155
	v_pk_add_f32 v[148:149], v[148:149], s[0:1] op_sel:[0,1] op_sel_hi:[1,1]
	v_pk_add_f32 v[150:151], v[150:151], s[0:1] op_sel:[0,1] op_sel_hi:[1,1]
	v_pk_add_f32 v[152:153], v[152:153], s[0:1] op_sel:[0,1] op_sel_hi:[1,1]
	v_pk_add_f32 v[154:155], v[154:155], s[0:1] op_sel:[0,1] op_sel_hi:[1,1]
	v_rcp_f32_e32 v148, v148
	v_rcp_f32_e32 v149, v149
	v_rcp_f32_e32 v150, v150
	v_rcp_f32_e32 v151, v151
	v_rcp_f32_e32 v152, v152
	v_rcp_f32_e32 v153, v153
	v_rcp_f32_e32 v154, v154
	v_rcp_f32_e32 v155, v155
	v_max_f32_e32 v148, 0x1e3ce508, v148
	v_max_f32_e32 v149, 0x1e3ce508, v149
	v_max_f32_e32 v150, 0x1e3ce508, v150
	v_max_f32_e32 v151, 0x1e3ce508, v151
	v_max_f32_e32 v152, 0x1e3ce508, v152
	v_max_f32_e32 v153, 0x1e3ce508, v153
	v_max_f32_e32 v154, 0x1e3ce508, v154
	v_max_f32_e32 v155, 0x1e3ce508, v155
	v_cvt_pk_bf16_f32 v132, v148, v149
	v_cvt_pk_bf16_f32 v133, v150, v151
	v_cvt_pk_bf16_f32 v134, v152, v153
	v_cvt_pk_bf16_f32 v135, v154, v155
	flat_store_dwordx4 v[130:131], v[132:135] nt
	v_lshl_add_u64 v[130:131], v[130:131], 0, s[6:7]
	v_pk_mul_f32 v[148:149], v[62:63], s[0:1] op_sel_hi:[1,0]
	v_pk_mul_f32 v[150:151], v[64:65], s[0:1] op_sel_hi:[1,0]
	v_pk_mul_f32 v[152:153], v[58:59], s[0:1] op_sel_hi:[1,0]
	v_pk_mul_f32 v[154:155], v[60:61], s[0:1] op_sel_hi:[1,0]
	v_exp_f32_e32 v148, v148
	v_exp_f32_e32 v149, v149
	v_exp_f32_e32 v150, v150
	v_exp_f32_e32 v151, v151
	v_exp_f32_e32 v152, v152
	v_exp_f32_e32 v153, v153
	v_exp_f32_e32 v154, v154
	v_exp_f32_e32 v155, v155
	v_pk_add_f32 v[148:149], v[148:149], s[0:1] op_sel:[0,1] op_sel_hi:[1,1]
	v_pk_add_f32 v[150:151], v[150:151], s[0:1] op_sel:[0,1] op_sel_hi:[1,1]
	v_pk_add_f32 v[152:153], v[152:153], s[0:1] op_sel:[0,1] op_sel_hi:[1,1]
	v_pk_add_f32 v[154:155], v[154:155], s[0:1] op_sel:[0,1] op_sel_hi:[1,1]
	v_rcp_f32_e32 v148, v148
	v_rcp_f32_e32 v149, v149
	v_rcp_f32_e32 v150, v150
	v_rcp_f32_e32 v151, v151
	v_rcp_f32_e32 v152, v152
	v_rcp_f32_e32 v153, v153
	v_rcp_f32_e32 v154, v154
	v_rcp_f32_e32 v155, v155
	v_max_f32_e32 v148, 0x1e3ce508, v148
	v_max_f32_e32 v149, 0x1e3ce508, v149
	v_max_f32_e32 v150, 0x1e3ce508, v150
	v_max_f32_e32 v151, 0x1e3ce508, v151
	v_max_f32_e32 v152, 0x1e3ce508, v152
	v_max_f32_e32 v153, 0x1e3ce508, v153
	v_max_f32_e32 v154, 0x1e3ce508, v154
	v_max_f32_e32 v155, 0x1e3ce508, v155
	v_cvt_pk_bf16_f32 v132, v148, v149
	v_cvt_pk_bf16_f32 v133, v150, v151
	v_cvt_pk_bf16_f32 v134, v152, v153
	v_cvt_pk_bf16_f32 v135, v154, v155
	flat_store_dwordx4 v[130:131], v[132:135] nt
	v_lshl_add_u64 v[130:131], v[130:131], 0, s[6:7]
	v_pk_mul_f32 v[148:149], v[30:31], s[0:1] op_sel_hi:[1,0]
	v_pk_mul_f32 v[150:151], v[32:33], s[0:1] op_sel_hi:[1,0]
	v_pk_mul_f32 v[152:153], v[26:27], s[0:1] op_sel_hi:[1,0]
	v_pk_mul_f32 v[154:155], v[28:29], s[0:1] op_sel_hi:[1,0]
	v_exp_f32_e32 v148, v148
	v_exp_f32_e32 v149, v149
	v_exp_f32_e32 v150, v150
	v_exp_f32_e32 v151, v151
	v_exp_f32_e32 v152, v152
	v_exp_f32_e32 v153, v153
	v_exp_f32_e32 v154, v154
	v_exp_f32_e32 v155, v155
	v_pk_add_f32 v[148:149], v[148:149], s[0:1] op_sel:[0,1] op_sel_hi:[1,1]
	v_pk_add_f32 v[150:151], v[150:151], s[0:1] op_sel:[0,1] op_sel_hi:[1,1]
	v_pk_add_f32 v[152:153], v[152:153], s[0:1] op_sel:[0,1] op_sel_hi:[1,1]
	v_pk_add_f32 v[154:155], v[154:155], s[0:1] op_sel:[0,1] op_sel_hi:[1,1]
	v_rcp_f32_e32 v148, v148
	v_rcp_f32_e32 v149, v149
	v_rcp_f32_e32 v150, v150
	v_rcp_f32_e32 v151, v151
	v_rcp_f32_e32 v152, v152
	v_rcp_f32_e32 v153, v153
	v_rcp_f32_e32 v154, v154
	v_rcp_f32_e32 v155, v155
	v_max_f32_e32 v148, 0x1e3ce508, v148
	v_max_f32_e32 v149, 0x1e3ce508, v149
	v_max_f32_e32 v150, 0x1e3ce508, v150
	v_max_f32_e32 v151, 0x1e3ce508, v151
	v_max_f32_e32 v152, 0x1e3ce508, v152
	v_max_f32_e32 v153, 0x1e3ce508, v153
	v_max_f32_e32 v154, 0x1e3ce508, v154
	v_max_f32_e32 v155, 0x1e3ce508, v155
	v_cvt_pk_bf16_f32 v132, v148, v149
	v_cvt_pk_bf16_f32 v133, v150, v151
	v_cvt_pk_bf16_f32 v134, v152, v153
	v_cvt_pk_bf16_f32 v135, v154, v155
	flat_store_dwordx4 v[130:131], v[132:135] nt
	v_lshl_add_u64 v[130:131], v[130:131], 0, s[6:7]
	v_pk_mul_f32 v[148:149], v[54:55], s[0:1] op_sel_hi:[1,0]
	v_pk_mul_f32 v[150:151], v[56:57], s[0:1] op_sel_hi:[1,0]
	v_pk_mul_f32 v[152:153], v[50:51], s[0:1] op_sel_hi:[1,0]
	v_pk_mul_f32 v[154:155], v[52:53], s[0:1] op_sel_hi:[1,0]
	v_exp_f32_e32 v148, v148
	v_exp_f32_e32 v149, v149
	v_exp_f32_e32 v150, v150
	v_exp_f32_e32 v151, v151
	v_exp_f32_e32 v152, v152
	v_exp_f32_e32 v153, v153
	v_exp_f32_e32 v154, v154
	v_exp_f32_e32 v155, v155
	v_pk_add_f32 v[148:149], v[148:149], s[0:1] op_sel:[0,1] op_sel_hi:[1,1]
	v_pk_add_f32 v[150:151], v[150:151], s[0:1] op_sel:[0,1] op_sel_hi:[1,1]
	v_pk_add_f32 v[152:153], v[152:153], s[0:1] op_sel:[0,1] op_sel_hi:[1,1]
	v_pk_add_f32 v[154:155], v[154:155], s[0:1] op_sel:[0,1] op_sel_hi:[1,1]
	v_rcp_f32_e32 v148, v148
	v_rcp_f32_e32 v149, v149
	v_rcp_f32_e32 v150, v150
	v_rcp_f32_e32 v151, v151
	v_rcp_f32_e32 v152, v152
	v_rcp_f32_e32 v153, v153
	v_rcp_f32_e32 v154, v154
	v_rcp_f32_e32 v155, v155
	v_max_f32_e32 v148, 0x1e3ce508, v148
	v_max_f32_e32 v149, 0x1e3ce508, v149
	v_max_f32_e32 v150, 0x1e3ce508, v150
	v_max_f32_e32 v151, 0x1e3ce508, v151
	v_max_f32_e32 v152, 0x1e3ce508, v152
	v_max_f32_e32 v153, 0x1e3ce508, v153
	v_max_f32_e32 v154, 0x1e3ce508, v154
	v_max_f32_e32 v155, 0x1e3ce508, v155
	v_cvt_pk_bf16_f32 v132, v148, v149
	v_cvt_pk_bf16_f32 v133, v150, v151
	v_cvt_pk_bf16_f32 v134, v152, v153
	v_cvt_pk_bf16_f32 v135, v154, v155
	flat_store_dwordx4 v[130:131], v[132:135] nt
	v_lshl_add_u64 v[130:131], v[130:131], 0, s[6:7]
	v_pk_mul_f32 v[148:149], v[22:23], s[0:1] op_sel_hi:[1,0]
	v_pk_mul_f32 v[150:151], v[24:25], s[0:1] op_sel_hi:[1,0]
	v_pk_mul_f32 v[152:153], v[18:19], s[0:1] op_sel_hi:[1,0]
	v_pk_mul_f32 v[154:155], v[20:21], s[0:1] op_sel_hi:[1,0]
	v_exp_f32_e32 v148, v148
	v_exp_f32_e32 v149, v149
	v_exp_f32_e32 v150, v150
	v_exp_f32_e32 v151, v151
	v_exp_f32_e32 v152, v152
	v_exp_f32_e32 v153, v153
	v_exp_f32_e32 v154, v154
	v_exp_f32_e32 v155, v155
	v_pk_add_f32 v[148:149], v[148:149], s[0:1] op_sel:[0,1] op_sel_hi:[1,1]
	v_pk_add_f32 v[150:151], v[150:151], s[0:1] op_sel:[0,1] op_sel_hi:[1,1]
	v_pk_add_f32 v[152:153], v[152:153], s[0:1] op_sel:[0,1] op_sel_hi:[1,1]
	v_pk_add_f32 v[154:155], v[154:155], s[0:1] op_sel:[0,1] op_sel_hi:[1,1]
	v_rcp_f32_e32 v148, v148
	v_rcp_f32_e32 v149, v149
	v_rcp_f32_e32 v150, v150
	v_rcp_f32_e32 v151, v151
	v_rcp_f32_e32 v152, v152
	v_rcp_f32_e32 v153, v153
	v_rcp_f32_e32 v154, v154
	v_rcp_f32_e32 v155, v155
	v_max_f32_e32 v148, 0x1e3ce508, v148
	v_max_f32_e32 v149, 0x1e3ce508, v149
	v_max_f32_e32 v150, 0x1e3ce508, v150
	v_max_f32_e32 v151, 0x1e3ce508, v151
	v_max_f32_e32 v152, 0x1e3ce508, v152
	v_max_f32_e32 v153, 0x1e3ce508, v153
	v_max_f32_e32 v154, 0x1e3ce508, v154
	v_max_f32_e32 v155, 0x1e3ce508, v155
	v_cvt_pk_bf16_f32 v132, v148, v149
	v_cvt_pk_bf16_f32 v133, v150, v151
	v_cvt_pk_bf16_f32 v134, v152, v153
	v_cvt_pk_bf16_f32 v135, v154, v155
	flat_store_dwordx4 v[130:131], v[132:135] nt
	v_lshl_add_u64 v[130:131], v[130:131], 0, s[6:7]
	v_pk_mul_f32 v[148:149], v[46:47], s[0:1] op_sel_hi:[1,0]
	v_pk_mul_f32 v[150:151], v[48:49], s[0:1] op_sel_hi:[1,0]
	v_pk_mul_f32 v[152:153], v[42:43], s[0:1] op_sel_hi:[1,0]
	v_pk_mul_f32 v[154:155], v[44:45], s[0:1] op_sel_hi:[1,0]
	v_exp_f32_e32 v148, v148
	v_exp_f32_e32 v149, v149
	v_exp_f32_e32 v150, v150
	v_exp_f32_e32 v151, v151
	v_exp_f32_e32 v152, v152
	v_exp_f32_e32 v153, v153
	v_exp_f32_e32 v154, v154
	v_exp_f32_e32 v155, v155
	v_pk_add_f32 v[148:149], v[148:149], s[0:1] op_sel:[0,1] op_sel_hi:[1,1]
	v_pk_add_f32 v[150:151], v[150:151], s[0:1] op_sel:[0,1] op_sel_hi:[1,1]
	v_pk_add_f32 v[152:153], v[152:153], s[0:1] op_sel:[0,1] op_sel_hi:[1,1]
	v_pk_add_f32 v[154:155], v[154:155], s[0:1] op_sel:[0,1] op_sel_hi:[1,1]
	v_rcp_f32_e32 v148, v148
	v_rcp_f32_e32 v149, v149
	v_rcp_f32_e32 v150, v150
	v_rcp_f32_e32 v151, v151
	v_rcp_f32_e32 v152, v152
	v_rcp_f32_e32 v153, v153
	v_rcp_f32_e32 v154, v154
	v_rcp_f32_e32 v155, v155
	v_max_f32_e32 v148, 0x1e3ce508, v148
	v_max_f32_e32 v149, 0x1e3ce508, v149
	v_max_f32_e32 v150, 0x1e3ce508, v150
	v_max_f32_e32 v151, 0x1e3ce508, v151
	v_max_f32_e32 v152, 0x1e3ce508, v152
	v_max_f32_e32 v153, 0x1e3ce508, v153
	v_max_f32_e32 v154, 0x1e3ce508, v154
	v_max_f32_e32 v155, 0x1e3ce508, v155
	v_cvt_pk_bf16_f32 v132, v148, v149
	v_cvt_pk_bf16_f32 v133, v150, v151
	v_cvt_pk_bf16_f32 v134, v152, v153
	v_cvt_pk_bf16_f32 v135, v154, v155
	flat_store_dwordx4 v[130:131], v[132:135] nt
	v_lshl_add_u64 v[130:131], v[130:131], 0, s[6:7]
	v_pk_mul_f32 v[148:149], v[14:15], s[0:1] op_sel_hi:[1,0]
	v_pk_mul_f32 v[150:151], v[16:17], s[0:1] op_sel_hi:[1,0]
	v_pk_mul_f32 v[152:153], v[10:11], s[0:1] op_sel_hi:[1,0]
	v_pk_mul_f32 v[154:155], v[12:13], s[0:1] op_sel_hi:[1,0]
	v_exp_f32_e32 v148, v148
	v_exp_f32_e32 v149, v149
	v_exp_f32_e32 v150, v150
	v_exp_f32_e32 v151, v151
	v_exp_f32_e32 v152, v152
	v_exp_f32_e32 v153, v153
	v_exp_f32_e32 v154, v154
	v_exp_f32_e32 v155, v155
	v_pk_add_f32 v[148:149], v[148:149], s[0:1] op_sel:[0,1] op_sel_hi:[1,1]
	v_pk_add_f32 v[150:151], v[150:151], s[0:1] op_sel:[0,1] op_sel_hi:[1,1]
	v_pk_add_f32 v[152:153], v[152:153], s[0:1] op_sel:[0,1] op_sel_hi:[1,1]
	v_pk_add_f32 v[154:155], v[154:155], s[0:1] op_sel:[0,1] op_sel_hi:[1,1]
	v_rcp_f32_e32 v148, v148
	v_rcp_f32_e32 v149, v149
	v_rcp_f32_e32 v150, v150
	v_rcp_f32_e32 v151, v151
	v_rcp_f32_e32 v152, v152
	v_rcp_f32_e32 v153, v153
	v_rcp_f32_e32 v154, v154
	v_rcp_f32_e32 v155, v155
	v_max_f32_e32 v148, 0x1e3ce508, v148
	v_max_f32_e32 v149, 0x1e3ce508, v149
	v_max_f32_e32 v150, 0x1e3ce508, v150
	v_max_f32_e32 v151, 0x1e3ce508, v151
	v_max_f32_e32 v152, 0x1e3ce508, v152
	v_max_f32_e32 v153, 0x1e3ce508, v153
	v_max_f32_e32 v154, 0x1e3ce508, v154
	v_max_f32_e32 v155, 0x1e3ce508, v155
	v_cvt_pk_bf16_f32 v132, v148, v149
	v_cvt_pk_bf16_f32 v133, v150, v151
	v_cvt_pk_bf16_f32 v134, v152, v153
	v_cvt_pk_bf16_f32 v135, v154, v155
	flat_store_dwordx4 v[130:131], v[132:135] nt
	v_lshl_add_u64 v[130:131], v[130:131], 0, s[6:7]
	v_pk_mul_f32 v[148:149], v[38:39], s[0:1] op_sel_hi:[1,0]
	v_pk_mul_f32 v[150:151], v[40:41], s[0:1] op_sel_hi:[1,0]
	v_pk_mul_f32 v[152:153], v[34:35], s[0:1] op_sel_hi:[1,0]
	v_pk_mul_f32 v[154:155], v[36:37], s[0:1] op_sel_hi:[1,0]
	v_exp_f32_e32 v148, v148
	v_exp_f32_e32 v149, v149
	v_exp_f32_e32 v150, v150
	v_exp_f32_e32 v151, v151
	v_exp_f32_e32 v152, v152
	v_exp_f32_e32 v153, v153
	v_exp_f32_e32 v154, v154
	v_exp_f32_e32 v155, v155
	v_pk_add_f32 v[148:149], v[148:149], s[0:1] op_sel:[0,1] op_sel_hi:[1,1]
	v_pk_add_f32 v[150:151], v[150:151], s[0:1] op_sel:[0,1] op_sel_hi:[1,1]
	v_pk_add_f32 v[152:153], v[152:153], s[0:1] op_sel:[0,1] op_sel_hi:[1,1]
	v_pk_add_f32 v[154:155], v[154:155], s[0:1] op_sel:[0,1] op_sel_hi:[1,1]
	v_rcp_f32_e32 v148, v148
	v_rcp_f32_e32 v149, v149
	v_rcp_f32_e32 v150, v150
	v_rcp_f32_e32 v151, v151
	v_rcp_f32_e32 v152, v152
	v_rcp_f32_e32 v153, v153
	v_rcp_f32_e32 v154, v154
	v_rcp_f32_e32 v155, v155
	v_max_f32_e32 v148, 0x1e3ce508, v148
	v_max_f32_e32 v149, 0x1e3ce508, v149
	v_max_f32_e32 v150, 0x1e3ce508, v150
	v_max_f32_e32 v151, 0x1e3ce508, v151
	v_max_f32_e32 v152, 0x1e3ce508, v152
	v_max_f32_e32 v153, 0x1e3ce508, v153
	v_max_f32_e32 v154, 0x1e3ce508, v154
	v_max_f32_e32 v155, 0x1e3ce508, v155
	v_cvt_pk_bf16_f32 v132, v148, v149
	v_cvt_pk_bf16_f32 v133, v150, v151
	v_cvt_pk_bf16_f32 v134, v152, v153
	v_cvt_pk_bf16_f32 v135, v154, v155
	flat_store_dwordx4 v[130:131], v[132:135] nt
	v_lshl_add_u64 v[130:131], v[130:131], 0, s[6:7]
	v_pk_mul_f32 v[148:149], v[6:7], s[0:1] op_sel_hi:[1,0]
	v_pk_mul_f32 v[150:151], v[8:9], s[0:1] op_sel_hi:[1,0]
	v_pk_mul_f32 v[152:153], v[2:3], s[0:1] op_sel_hi:[1,0]
	v_pk_mul_f32 v[154:155], v[4:5], s[0:1] op_sel_hi:[1,0]
	v_exp_f32_e32 v148, v148
	v_exp_f32_e32 v149, v149
	v_exp_f32_e32 v150, v150
	v_exp_f32_e32 v151, v151
	v_exp_f32_e32 v152, v152
	v_exp_f32_e32 v153, v153
	v_exp_f32_e32 v154, v154
	v_exp_f32_e32 v155, v155
	v_pk_add_f32 v[148:149], v[148:149], s[0:1] op_sel:[0,1] op_sel_hi:[1,1]
	v_pk_add_f32 v[150:151], v[150:151], s[0:1] op_sel:[0,1] op_sel_hi:[1,1]
	v_pk_add_f32 v[152:153], v[152:153], s[0:1] op_sel:[0,1] op_sel_hi:[1,1]
	v_pk_add_f32 v[154:155], v[154:155], s[0:1] op_sel:[0,1] op_sel_hi:[1,1]
	v_rcp_f32_e32 v148, v148
	v_rcp_f32_e32 v149, v149
	v_rcp_f32_e32 v150, v150
	v_rcp_f32_e32 v151, v151
	v_rcp_f32_e32 v152, v152
	v_rcp_f32_e32 v153, v153
	v_rcp_f32_e32 v154, v154
	v_rcp_f32_e32 v155, v155
	v_max_f32_e32 v148, 0x1e3ce508, v148
	v_max_f32_e32 v149, 0x1e3ce508, v149
	v_max_f32_e32 v150, 0x1e3ce508, v150
	v_max_f32_e32 v151, 0x1e3ce508, v151
	v_max_f32_e32 v152, 0x1e3ce508, v152
	v_max_f32_e32 v153, 0x1e3ce508, v153
	v_max_f32_e32 v154, 0x1e3ce508, v154
	v_max_f32_e32 v155, 0x1e3ce508, v155
	v_cvt_pk_bf16_f32 v132, v148, v149
	v_cvt_pk_bf16_f32 v133, v150, v151
	v_cvt_pk_bf16_f32 v134, v152, v153
	v_cvt_pk_bf16_f32 v135, v154, v155
	flat_store_dwordx4 v[130:131], v[132:135] nt
	s_mov_b64 s[0:1], 0

.LBB0_1121:
	v_lshl_add_u32 v0, s70, 8, v149
	v_mad_i64_i32 v[130:131], s[0:1], v0, s36, 0
	s_lshl_b32 s0, s69, 8
	v_lshl_add_u64 v[130:131], v[130:131], 1, s[34:35]
	s_ashr_i32 s1, s0, 31
	v_lshl_add_u64 v[130:131], s[0:1], 1, v[130:131]
	v_ashrrev_i32_e32 v149, 31, v148
	s_ashr_i32 s37, s36, 31
	v_lshl_add_u64 v[134:135], v[148:149], 1, v[130:131]
	v_cvt_pk_bf16_f32 v130, v126, v127
	v_cvt_pk_bf16_f32 v131, v128, v129
	v_cvt_pk_bf16_f32 v132, v122, v123
	v_cvt_pk_bf16_f32 v133, v124, v125
	flat_store_dwordx4 v[134:135], v[130:133] nt
	s_lshl_b64 s[0:1], s[36:37], 5
	v_mov_b32_e32 v0, 0xa0
	v_cvt_pk_bf16_f32 v130, v94, v95
	v_cvt_pk_bf16_f32 v131, v96, v97
	v_cvt_pk_bf16_f32 v132, v90, v91
	v_cvt_pk_bf16_f32 v133, v92, v93
	flat_store_dwordx4 v[134:135], v[130:133] offset:256 nt
	v_lshl_add_u64 v[134:135], v[134:135], 0, s[0:1]
	s_nop 0
	v_cvt_pk_bf16_f32 v130, v118, v119
	v_cvt_pk_bf16_f32 v131, v120, v121
	v_cvt_pk_bf16_f32 v132, v114, v115
	v_cvt_pk_bf16_f32 v133, v116, v117
	flat_store_dwordx4 v[134:135], v[130:133] nt
	s_nop 1
	v_cvt_pk_bf16_f32 v130, v86, v87
	v_cvt_pk_bf16_f32 v131, v88, v89
	v_cvt_pk_bf16_f32 v132, v82, v83
	v_cvt_pk_bf16_f32 v133, v84, v85
	flat_store_dwordx4 v[134:135], v[130:133] offset:256 nt
	v_lshl_add_u64 v[134:135], v[134:135], 0, s[0:1]
	s_nop 0
	v_cvt_pk_bf16_f32 v130, v110, v111
	v_cvt_pk_bf16_f32 v131, v112, v113
	v_cvt_pk_bf16_f32 v132, v106, v107
	v_cvt_pk_bf16_f32 v133, v108, v109
	flat_store_dwordx4 v[134:135], v[130:133] nt
	s_nop 1
	v_cvt_pk_bf16_f32 v130, v78, v79
	v_cvt_pk_bf16_f32 v131, v80, v81
	v_cvt_pk_bf16_f32 v132, v74, v75
	v_cvt_pk_bf16_f32 v133, v76, v77
	flat_store_dwordx4 v[134:135], v[130:133] offset:256 nt
	v_lshl_add_u64 v[134:135], v[134:135], 0, s[0:1]
	s_nop 0
	v_cvt_pk_bf16_f32 v130, v102, v103
	v_cvt_pk_bf16_f32 v131, v104, v105
	v_cvt_pk_bf16_f32 v132, v98, v99
	v_cvt_pk_bf16_f32 v133, v100, v101
	flat_store_dwordx4 v[134:135], v[130:133] nt
	s_nop 1
	v_cvt_pk_bf16_f32 v130, v70, v71
	v_cvt_pk_bf16_f32 v131, v72, v73
	v_cvt_pk_bf16_f32 v132, v66, v67
	v_cvt_pk_bf16_f32 v133, v68, v69
	flat_store_dwordx4 v[134:135], v[130:133] offset:256 nt
	v_mad_i64_i32 v[134:135], s[2:3], s36, v0, v[134:135]
	s_nop 0
	v_cvt_pk_bf16_f32 v130, v62, v63
	v_cvt_pk_bf16_f32 v131, v64, v65
	v_cvt_pk_bf16_f32 v132, v58, v59
	v_cvt_pk_bf16_f32 v133, v60, v61
	flat_store_dwordx4 v[134:135], v[130:133] nt
	s_nop 1
	v_cvt_pk_bf16_f32 v130, v30, v31
	v_cvt_pk_bf16_f32 v131, v32, v33
	v_cvt_pk_bf16_f32 v132, v26, v27
	v_cvt_pk_bf16_f32 v133, v28, v29
	flat_store_dwordx4 v[134:135], v[130:133] offset:256 nt
	v_lshl_add_u64 v[134:135], v[134:135], 0, s[0:1]
	s_nop 0
	v_cvt_pk_bf16_f32 v130, v54, v55
	v_cvt_pk_bf16_f32 v131, v56, v57
	v_cvt_pk_bf16_f32 v132, v50, v51
	v_cvt_pk_bf16_f32 v133, v52, v53
	flat_store_dwordx4 v[134:135], v[130:133] nt
	s_nop 1
	v_cvt_pk_bf16_f32 v130, v22, v23
	v_cvt_pk_bf16_f32 v131, v24, v25
	v_cvt_pk_bf16_f32 v132, v18, v19
	v_cvt_pk_bf16_f32 v133, v20, v21
	flat_store_dwordx4 v[134:135], v[130:133] offset:256 nt
	v_lshl_add_u64 v[134:135], v[134:135], 0, s[0:1]
	s_nop 0
	v_cvt_pk_bf16_f32 v130, v46, v47
	v_cvt_pk_bf16_f32 v131, v48, v49
	v_cvt_pk_bf16_f32 v132, v42, v43
	v_cvt_pk_bf16_f32 v133, v44, v45
	flat_store_dwordx4 v[134:135], v[130:133] nt
	s_nop 1
	v_cvt_pk_bf16_f32 v130, v14, v15
	v_cvt_pk_bf16_f32 v131, v16, v17
	v_cvt_pk_bf16_f32 v132, v10, v11
	v_cvt_pk_bf16_f32 v133, v12, v13
	flat_store_dwordx4 v[134:135], v[130:133] offset:256 nt
	v_lshl_add_u64 v[134:135], v[134:135], 0, s[0:1]
	s_nop 0
	v_cvt_pk_bf16_f32 v130, v38, v39
	v_cvt_pk_bf16_f32 v131, v40, v41
	v_cvt_pk_bf16_f32 v132, v34, v35
	v_cvt_pk_bf16_f32 v133, v36, v37
	flat_store_dwordx4 v[134:135], v[130:133] nt
	s_nop 1
	v_cvt_pk_bf16_f32 v130, v6, v7
	v_cvt_pk_bf16_f32 v131, v8, v9
	v_cvt_pk_bf16_f32 v132, v2, v3
	v_cvt_pk_bf16_f32 v133, v4, v5
	flat_store_dwordx4 v[134:135], v[130:133] offset:256 nt
	s_add_u32 s0, s74, 0xffffff00
	s_addc_u32 s1, s75, -1
	s_andn2_b64 vcc, exec, s[4:5]
	s_cbranch_vccz .LBB0_1119

.LBB0_1127:
	v_readlane_b32 s18, v253, 31
	v_readlane_b32 s50, v253, 17
	s_cmp_lg_u32 s18, 18
	v_readlane_b32 s48, v253, 16
	v_readlane_b32 s51, v253, 18
	s_cbranch_scc1 .LBB0_1130
	v_mov_b32_e32 v0, v216
	s_mov_b64 s[0:1], 0x5800000
	v_and_b32_e32 v4, 63, v0
	v_ashrrev_i32_e32 v5, 6, v0
	v_xor_b32_e32 v0, 1, v219
	v_cmp_lt_i32_e32 vcc, v0, v223
	s_mov_b32 s2, 0
	s_nop 0
	v_cndmask_b32_e32 v0, v219, v0, vcc
	v_lshlrev_b32_e32 v30, 2, v0
	v_xor_b32_e32 v0, 2, v219
	v_cmp_lt_i32_e32 vcc, v0, v223
	s_nop 1
	v_cndmask_b32_e32 v0, v219, v0, vcc
	v_lshlrev_b32_e32 v31, 2, v0
	v_xor_b32_e32 v0, 4, v219
	v_cmp_lt_i32_e32 vcc, v0, v223
	s_nop 1
	v_cndmask_b32_e32 v0, v219, v0, vcc
	v_lshlrev_b32_e32 v32, 2, v0
	v_xor_b32_e32 v0, 8, v219
	v_cmp_lt_i32_e32 vcc, v0, v223
	s_nop 1
	v_cndmask_b32_e32 v0, v219, v0, vcc
	v_cmp_lt_i32_e32 vcc, v221, v223
	v_lshlrev_b32_e32 v33, 2, v0
	s_nop 0
	v_cndmask_b32_e32 v0, v219, v221, vcc
	v_cmp_lt_i32_e32 vcc, v224, v223
	v_lshlrev_b32_e32 v34, 2, v0
	s_nop 0
	v_cndmask_b32_e32 v0, v219, v224, vcc
	v_lshlrev_b32_e32 v35, 2, v0
	v_lshlrev_b32_e32 v0, 3, v4
	v_lshl_add_u64 v[2:3], s[82:83], 0, v[0:1]
	v_lshl_add_u64 v[18:19], v[2:3], 0, s[0:1]
	s_mov_b64 s[0:1], 0x1b000000
	v_lshl_add_u64 v[24:25], v[2:3], 0, s[0:1]
	v_readlane_b32 s0, v253, 19
	v_readlane_b32 s1, v253, 21
	s_lshl_b32 s0, s0, 8
	s_lshl_b32 s1, s1, 6
	v_lshlrev_b32_e32 v0, 4, v4
	s_add_i32 s1, s1, s0
	v_readlane_b32 s0, v253, 24
	v_lshl_add_u64 v[20:21], s[52:53], 0, v[0:1]
	v_lshl_add_u64 v[22:23], s[58:59], 0, v[0:1]
	v_add_u32_e32 v0, s1, v5
	s_lshl_b32 s0, s0, 8
	v_subrev_u32_e32 v0, s0, v0
	v_readlane_b32 s0, v253, 20
	s_lshl_b32 s0, s0, 6
	s_nop 0
	v_subrev_u32_e32 v0, s0, v0
	v_readlane_b32 s0, v253, 32
	s_nop 1
	v_subrev_u32_e32 v0, s0, v0
	v_add_co_u32_e32 v134, vcc, 0x4000000, v20
	s_nop 1
	v_addc_co_u32_e32 v135, vcc, 0, v21, vcc
	v_add_co_u32_e32 v136, vcc, 0x2000000, v24
	s_nop 1
	v_addc_co_u32_e32 v137, vcc, 0, v25, vcc
	global_load_dwordx4 v[64:67], v[22:23], off offset:0
	global_load_dwordx4 v[68:71], v[22:23], off offset:1024
	global_load_dwordx4 v[72:75], v[22:23], off offset:2048
	global_load_dwordx4 v[76:79], v[22:23], off offset:3072
	v_mov_b32_e32 v132, v0
	v_ashrrev_i32_e32 v133, 31, v132
	v_lshlrev_b64 v[138:139], 12, v[132:133]
	v_lshl_add_u64 v[2:3], v[134:135], 0, v[138:139]
	global_load_dwordx4 v[80:83], v[2:3], off offset:0
	global_load_dwordx4 v[84:87], v[2:3], off offset:1024
	global_load_dwordx4 v[88:91], v[2:3], off offset:2048
	global_load_dwordx4 v[92:95], v[2:3], off offset:3072
	v_add_u32_e32 v132, 8, v0
	v_ashrrev_i32_e32 v133, 31, v132
	v_lshlrev_b64 v[138:139], 12, v[132:133]
	v_lshl_add_u64 v[2:3], v[134:135], 0, v[138:139]
	global_load_dwordx4 v[96:99], v[2:3], off offset:0
	global_load_dwordx4 v[100:103], v[2:3], off offset:1024
	global_load_dwordx4 v[104:107], v[2:3], off offset:2048
	global_load_dwordx4 v[108:111], v[2:3], off offset:3072
	v_mov_b32_e32 v132, v0
	v_ashrrev_i32_e32 v133, 31, v132
	v_lshlrev_b64 v[138:139], 11, v[132:133]
	v_lshl_add_u64 v[128:129], v[18:19], 0, v[138:139]
	v_lshl_add_u64 v[130:131], v[136:137], 0, v[138:139]
	s_waitcnt vmcnt(4)
	v_mul_f32_e32 v112, v81, v81
	v_mul_f32_e32 v113, v85, v85
	v_mul_f32_e32 v114, v89, v89
	v_mul_f32_e32 v115, v93, v93
	v_fmac_f32_e32 v112, v80, v80
	v_fmac_f32_e32 v113, v84, v84
	v_fmac_f32_e32 v114, v88, v88
	v_fmac_f32_e32 v115, v92, v92
	v_fmac_f32_e32 v112, v82, v82
	v_fmac_f32_e32 v113, v86, v86
	v_fmac_f32_e32 v114, v90, v90
	v_fmac_f32_e32 v115, v94, v94
	v_fmac_f32_e32 v112, v83, v83
	v_fmac_f32_e32 v113, v87, v87
	v_fmac_f32_e32 v114, v91, v91
	v_fmac_f32_e32 v115, v95, v95
	v_add_f32_e32 v116, v112, v113
	v_add_f32_e32 v116, v116, v114
	v_add_f32_e32 v116, v116, v115
	ds_bpermute_b32 v117, v30, v116
	s_waitcnt lgkmcnt(0)
	v_add_f32_e32 v116, v116, v117
	ds_bpermute_b32 v117, v31, v116
	s_waitcnt lgkmcnt(0)
	v_add_f32_e32 v116, v116, v117
	ds_bpermute_b32 v117, v32, v116
	s_waitcnt lgkmcnt(0)
	v_add_f32_e32 v116, v116, v117
	ds_bpermute_b32 v117, v33, v116
	s_waitcnt lgkmcnt(0)
	v_add_f32_e32 v116, v116, v117
	ds_bpermute_b32 v117, v34, v116
	s_waitcnt lgkmcnt(0)
	v_add_f32_e32 v116, v116, v117
	ds_bpermute_b32 v117, v35, v116
	s_waitcnt lgkmcnt(0)
	v_add_f32_e32 v116, v116, v117
	v_fmamk_f32 v116, v116, 0x3a800000, v217
	v_mul_f32_e32 v117, 0x4f800000, v116
	v_cmp_gt_f32_e32 vcc, s36, v116
	s_nop 1
	v_cndmask_b32_e32 v116, v116, v117, vcc
	v_sqrt_f32_e32 v117, v116
	s_nop 0
	v_add_u32_e32 v118, -1, v117
	v_add_u32_e32 v119, 1, v117
	v_fma_f32 v120, -v118, v117, v116
	v_fma_f32 v121, -v119, v117, v116
	v_cmp_ge_f32_e64 s[0:1], 0, v120
	s_nop 1
	v_cndmask_b32_e64 v117, v117, v118, s[0:1]
	v_cmp_lt_f32_e64 s[0:1], 0, v121
	s_nop 1
	v_cndmask_b32_e64 v117, v117, v119, s[0:1]
	v_mul_f32_e32 v118, 0x37800000, v117
	v_cndmask_b32_e32 v117, v117, v118, vcc
	v_cmp_class_f32_e32 vcc, v116, v218
	s_nop 1
	v_cndmask_b32_e32 v116, v117, v116, vcc
	v_div_scale_f32 v117, s[0:1], v116, v116, 1.0
	v_rcp_f32_e32 v119, v117
	v_div_scale_f32 v118, vcc, 1.0, v116, 1.0
	v_fma_f32 v120, -v117, v119, 1.0
	v_fmac_f32_e32 v119, v120, v119
	v_mul_f32_e32 v120, v118, v119
	v_fma_f32 v121, -v117, v120, v118
	v_fmac_f32_e32 v120, v121, v119
	v_fma_f32 v117, -v117, v120, v118
	v_div_fmas_f32 v117, v117, v119, v120
	v_div_fixup_f32 v122, v117, v116, 1.0
	v_cvt_pk_bf16_f32 v126, v80, v81
	v_cvt_pk_bf16_f32 v127, v82, v83
	global_store_dwordx2 v[130:131], v[126:127], off offset:0 nt
	v_mul_f32_e32 v80, v80, v122
	v_mul_f32_e32 v81, v81, v122
	v_mul_f32_e32 v82, v82, v122
	v_mul_f32_e32 v83, v83, v122
	v_mul_f32_e32 v80, v64, v80
	v_mul_f32_e32 v81, v65, v81
	v_mul_f32_e32 v82, v66, v82
	v_mul_f32_e32 v83, v67, v83
	v_cvt_pk_bf16_f32 v124, v80, v81
	v_cvt_pk_bf16_f32 v125, v82, v83
	global_store_dwordx2 v[128:129], v[124:125], off offset:0 nt
	v_cvt_pk_bf16_f32 v126, v84, v85
	v_cvt_pk_bf16_f32 v127, v86, v87
	global_store_dwordx2 v[130:131], v[126:127], off offset:512 nt
	v_mul_f32_e32 v84, v84, v122
	v_mul_f32_e32 v85, v85, v122
	v_mul_f32_e32 v86, v86, v122
	v_mul_f32_e32 v87, v87, v122
	v_mul_f32_e32 v84, v68, v84
	v_mul_f32_e32 v85, v69, v85
	v_mul_f32_e32 v86, v70, v86
	v_mul_f32_e32 v87, v71, v87
	v_cvt_pk_bf16_f32 v124, v84, v85
	v_cvt_pk_bf16_f32 v125, v86, v87
	global_store_dwordx2 v[128:129], v[124:125], off offset:512 nt
	v_cvt_pk_bf16_f32 v126, v88, v89
	v_cvt_pk_bf16_f32 v127, v90, v91
	global_store_dwordx2 v[130:131], v[126:127], off offset:1024 nt
	v_mul_f32_e32 v88, v88, v122
	v_mul_f32_e32 v89, v89, v122
	v_mul_f32_e32 v90, v90, v122
	v_mul_f32_e32 v91, v91, v122
	v_mul_f32_e32 v88, v72, v88
	v_mul_f32_e32 v89, v73, v89
	v_mul_f32_e32 v90, v74, v90
	v_mul_f32_e32 v91, v75, v91
	v_cvt_pk_bf16_f32 v124, v88, v89
	v_cvt_pk_bf16_f32 v125, v90, v91
	global_store_dwordx2 v[128:129], v[124:125], off offset:1024 nt
	v_cvt_pk_bf16_f32 v126, v92, v93
	v_cvt_pk_bf16_f32 v127, v94, v95
	global_store_dwordx2 v[130:131], v[126:127], off offset:1536 nt
	v_mul_f32_e32 v92, v92, v122
	v_mul_f32_e32 v93, v93, v122
	v_mul_f32_e32 v94, v94, v122
	v_mul_f32_e32 v95, v95, v122
	v_mul_f32_e32 v92, v76, v92
	v_mul_f32_e32 v93, v77, v93
	v_mul_f32_e32 v94, v78, v94
	v_mul_f32_e32 v95, v79, v95
	v_cvt_pk_bf16_f32 v124, v92, v93
	v_cvt_pk_bf16_f32 v125, v94, v95
	global_store_dwordx2 v[128:129], v[124:125], off offset:1536 nt
	v_add_u32_e32 v132, 16, v0
	v_ashrrev_i32_e32 v133, 31, v132
	v_lshlrev_b64 v[138:139], 12, v[132:133]
	v_lshl_add_u64 v[2:3], v[134:135], 0, v[138:139]
	global_load_dwordx4 v[80:83], v[2:3], off offset:0
	global_load_dwordx4 v[84:87], v[2:3], off offset:1024
	global_load_dwordx4 v[88:91], v[2:3], off offset:2048
	global_load_dwordx4 v[92:95], v[2:3], off offset:3072
	v_add_u32_e32 v132, 8, v0
	v_ashrrev_i32_e32 v133, 31, v132
	v_lshlrev_b64 v[138:139], 11, v[132:133]
	v_lshl_add_u64 v[128:129], v[18:19], 0, v[138:139]
	v_lshl_add_u64 v[130:131], v[136:137], 0, v[138:139]
	s_waitcnt vmcnt(12)
	v_mul_f32_e32 v112, v97, v97
	v_mul_f32_e32 v113, v101, v101
	v_mul_f32_e32 v114, v105, v105
	v_mul_f32_e32 v115, v109, v109
	v_fmac_f32_e32 v112, v96, v96
	v_fmac_f32_e32 v113, v100, v100
	v_fmac_f32_e32 v114, v104, v104
	v_fmac_f32_e32 v115, v108, v108
	v_fmac_f32_e32 v112, v98, v98
	v_fmac_f32_e32 v113, v102, v102
	v_fmac_f32_e32 v114, v106, v106
	v_fmac_f32_e32 v115, v110, v110
	v_fmac_f32_e32 v112, v99, v99
	v_fmac_f32_e32 v113, v103, v103
	v_fmac_f32_e32 v114, v107, v107
	v_fmac_f32_e32 v115, v111, v111
	v_add_f32_e32 v116, v112, v113
	v_add_f32_e32 v116, v116, v114
	v_add_f32_e32 v116, v116, v115
	ds_bpermute_b32 v117, v30, v116
	s_waitcnt lgkmcnt(0)
	v_add_f32_e32 v116, v116, v117
	ds_bpermute_b32 v117, v31, v116
	s_waitcnt lgkmcnt(0)
	v_add_f32_e32 v116, v116, v117
	ds_bpermute_b32 v117, v32, v116
	s_waitcnt lgkmcnt(0)
	v_add_f32_e32 v116, v116, v117
	ds_bpermute_b32 v117, v33, v116
	s_waitcnt lgkmcnt(0)
	v_add_f32_e32 v116, v116, v117
	ds_bpermute_b32 v117, v34, v116
	s_waitcnt lgkmcnt(0)
	v_add_f32_e32 v116, v116, v117
	ds_bpermute_b32 v117, v35, v116
	s_waitcnt lgkmcnt(0)
	v_add_f32_e32 v116, v116, v117
	v_fmamk_f32 v116, v116, 0x3a800000, v217
	v_mul_f32_e32 v117, 0x4f800000, v116
	v_cmp_gt_f32_e32 vcc, s36, v116
	s_nop 1
	v_cndmask_b32_e32 v116, v116, v117, vcc
	v_sqrt_f32_e32 v117, v116
	s_nop 0
	v_add_u32_e32 v118, -1, v117
	v_add_u32_e32 v119, 1, v117
	v_fma_f32 v120, -v118, v117, v116
	v_fma_f32 v121, -v119, v117, v116
	v_cmp_ge_f32_e64 s[0:1], 0, v120
	s_nop 1
	v_cndmask_b32_e64 v117, v117, v118, s[0:1]
	v_cmp_lt_f32_e64 s[0:1], 0, v121
	s_nop 1
	v_cndmask_b32_e64 v117, v117, v119, s[0:1]
	v_mul_f32_e32 v118, 0x37800000, v117
	v_cndmask_b32_e32 v117, v117, v118, vcc
	v_cmp_class_f32_e32 vcc, v116, v218
	s_nop 1
	v_cndmask_b32_e32 v116, v117, v116, vcc
	v_div_scale_f32 v117, s[0:1], v116, v116, 1.0
	v_rcp_f32_e32 v119, v117
	v_div_scale_f32 v118, vcc, 1.0, v116, 1.0
	v_fma_f32 v120, -v117, v119, 1.0
	v_fmac_f32_e32 v119, v120, v119
	v_mul_f32_e32 v120, v118, v119
	v_fma_f32 v121, -v117, v120, v118
	v_fmac_f32_e32 v120, v121, v119
	v_fma_f32 v117, -v117, v120, v118
	v_div_fmas_f32 v117, v117, v119, v120
	v_div_fixup_f32 v122, v117, v116, 1.0
	v_cvt_pk_bf16_f32 v126, v96, v97
	v_cvt_pk_bf16_f32 v127, v98, v99
	global_store_dwordx2 v[130:131], v[126:127], off offset:0 nt
	v_mul_f32_e32 v96, v96, v122
	v_mul_f32_e32 v97, v97, v122
	v_mul_f32_e32 v98, v98, v122
	v_mul_f32_e32 v99, v99, v122
	v_mul_f32_e32 v96, v64, v96
	v_mul_f32_e32 v97, v65, v97
	v_mul_f32_e32 v98, v66, v98
	v_mul_f32_e32 v99, v67, v99
	v_cvt_pk_bf16_f32 v124, v96, v97
	v_cvt_pk_bf16_f32 v125, v98, v99
	global_store_dwordx2 v[128:129], v[124:125], off offset:0 nt
	v_cvt_pk_bf16_f32 v126, v100, v101
	v_cvt_pk_bf16_f32 v127, v102, v103
	global_store_dwordx2 v[130:131], v[126:127], off offset:512 nt
	v_mul_f32_e32 v100, v100, v122
	v_mul_f32_e32 v101, v101, v122
	v_mul_f32_e32 v102, v102, v122
	v_mul_f32_e32 v103, v103, v122
	v_mul_f32_e32 v100, v68, v100
	v_mul_f32_e32 v101, v69, v101
	v_mul_f32_e32 v102, v70, v102
	v_mul_f32_e32 v103, v71, v103
	v_cvt_pk_bf16_f32 v124, v100, v101
	v_cvt_pk_bf16_f32 v125, v102, v103
	global_store_dwordx2 v[128:129], v[124:125], off offset:512 nt
	v_cvt_pk_bf16_f32 v126, v104, v105
	v_cvt_pk_bf16_f32 v127, v106, v107
	global_store_dwordx2 v[130:131], v[126:127], off offset:1024 nt
	v_mul_f32_e32 v104, v104, v122
	v_mul_f32_e32 v105, v105, v122
	v_mul_f32_e32 v106, v106, v122
	v_mul_f32_e32 v107, v107, v122
	v_mul_f32_e32 v104, v72, v104
	v_mul_f32_e32 v105, v73, v105
	v_mul_f32_e32 v106, v74, v106
	v_mul_f32_e32 v107, v75, v107
	v_cvt_pk_bf16_f32 v124, v104, v105
	v_cvt_pk_bf16_f32 v125, v106, v107
	global_store_dwordx2 v[128:129], v[124:125], off offset:1024 nt
	v_cvt_pk_bf16_f32 v126, v108, v109
	v_cvt_pk_bf16_f32 v127, v110, v111
	global_store_dwordx2 v[130:131], v[126:127], off offset:1536 nt
	v_mul_f32_e32 v108, v108, v122
	v_mul_f32_e32 v109, v109, v122
	v_mul_f32_e32 v110, v110, v122
	v_mul_f32_e32 v111, v111, v122
	v_mul_f32_e32 v108, v76, v108
	v_mul_f32_e32 v109, v77, v109
	v_mul_f32_e32 v110, v78, v110
	v_mul_f32_e32 v111, v79, v111
	v_cvt_pk_bf16_f32 v124, v108, v109
	v_cvt_pk_bf16_f32 v125, v110, v111
	global_store_dwordx2 v[128:129], v[124:125], off offset:1536 nt
	v_add_u32_e32 v132, 24, v0
	v_ashrrev_i32_e32 v133, 31, v132
	v_lshlrev_b64 v[138:139], 12, v[132:133]
	v_lshl_add_u64 v[2:3], v[134:135], 0, v[138:139]
	global_load_dwordx4 v[96:99], v[2:3], off offset:0
	global_load_dwordx4 v[100:103], v[2:3], off offset:1024
	global_load_dwordx4 v[104:107], v[2:3], off offset:2048
	global_load_dwordx4 v[108:111], v[2:3], off offset:3072
	v_add_u32_e32 v132, 16, v0
	v_ashrrev_i32_e32 v133, 31, v132
	v_lshlrev_b64 v[138:139], 11, v[132:133]
	v_lshl_add_u64 v[128:129], v[18:19], 0, v[138:139]
	v_lshl_add_u64 v[130:131], v[136:137], 0, v[138:139]
	s_waitcnt vmcnt(12)
	v_mul_f32_e32 v112, v81, v81
	v_mul_f32_e32 v113, v85, v85
	v_mul_f32_e32 v114, v89, v89
	v_mul_f32_e32 v115, v93, v93
	v_fmac_f32_e32 v112, v80, v80
	v_fmac_f32_e32 v113, v84, v84
	v_fmac_f32_e32 v114, v88, v88
	v_fmac_f32_e32 v115, v92, v92
	v_fmac_f32_e32 v112, v82, v82
	v_fmac_f32_e32 v113, v86, v86
	v_fmac_f32_e32 v114, v90, v90
	v_fmac_f32_e32 v115, v94, v94
	v_fmac_f32_e32 v112, v83, v83
	v_fmac_f32_e32 v113, v87, v87
	v_fmac_f32_e32 v114, v91, v91
	v_fmac_f32_e32 v115, v95, v95
	v_add_f32_e32 v116, v112, v113
	v_add_f32_e32 v116, v116, v114
	v_add_f32_e32 v116, v116, v115
	ds_bpermute_b32 v117, v30, v116
	s_waitcnt lgkmcnt(0)
	v_add_f32_e32 v116, v116, v117
	ds_bpermute_b32 v117, v31, v116
	s_waitcnt lgkmcnt(0)
	v_add_f32_e32 v116, v116, v117
	ds_bpermute_b32 v117, v32, v116
	s_waitcnt lgkmcnt(0)
	v_add_f32_e32 v116, v116, v117
	ds_bpermute_b32 v117, v33, v116
	s_waitcnt lgkmcnt(0)
	v_add_f32_e32 v116, v116, v117
	ds_bpermute_b32 v117, v34, v116
	s_waitcnt lgkmcnt(0)
	v_add_f32_e32 v116, v116, v117
	ds_bpermute_b32 v117, v35, v116
	s_waitcnt lgkmcnt(0)
	v_add_f32_e32 v116, v116, v117
	v_fmamk_f32 v116, v116, 0x3a800000, v217
	v_mul_f32_e32 v117, 0x4f800000, v116
	v_cmp_gt_f32_e32 vcc, s36, v116
	s_nop 1
	v_cndmask_b32_e32 v116, v116, v117, vcc
	v_sqrt_f32_e32 v117, v116
	s_nop 0
	v_add_u32_e32 v118, -1, v117
	v_add_u32_e32 v119, 1, v117
	v_fma_f32 v120, -v118, v117, v116
	v_fma_f32 v121, -v119, v117, v116
	v_cmp_ge_f32_e64 s[0:1], 0, v120
	s_nop 1
	v_cndmask_b32_e64 v117, v117, v118, s[0:1]
	v_cmp_lt_f32_e64 s[0:1], 0, v121
	s_nop 1
	v_cndmask_b32_e64 v117, v117, v119, s[0:1]
	v_mul_f32_e32 v118, 0x37800000, v117
	v_cndmask_b32_e32 v117, v117, v118, vcc
	v_cmp_class_f32_e32 vcc, v116, v218
	s_nop 1
	v_cndmask_b32_e32 v116, v117, v116, vcc
	v_div_scale_f32 v117, s[0:1], v116, v116, 1.0
	v_rcp_f32_e32 v119, v117
	v_div_scale_f32 v118, vcc, 1.0, v116, 1.0
	v_fma_f32 v120, -v117, v119, 1.0
	v_fmac_f32_e32 v119, v120, v119
	v_mul_f32_e32 v120, v118, v119
	v_fma_f32 v121, -v117, v120, v118
	v_fmac_f32_e32 v120, v121, v119
	v_fma_f32 v117, -v117, v120, v118
	v_div_fmas_f32 v117, v117, v119, v120
	v_div_fixup_f32 v122, v117, v116, 1.0
	v_cvt_pk_bf16_f32 v126, v80, v81
	v_cvt_pk_bf16_f32 v127, v82, v83
	global_store_dwordx2 v[130:131], v[126:127], off offset:0 nt
	v_mul_f32_e32 v80, v80, v122
	v_mul_f32_e32 v81, v81, v122
	v_mul_f32_e32 v82, v82, v122
	v_mul_f32_e32 v83, v83, v122
	v_mul_f32_e32 v80, v64, v80
	v_mul_f32_e32 v81, v65, v81
	v_mul_f32_e32 v82, v66, v82
	v_mul_f32_e32 v83, v67, v83
	v_cvt_pk_bf16_f32 v124, v80, v81
	v_cvt_pk_bf16_f32 v125, v82, v83
	global_store_dwordx2 v[128:129], v[124:125], off offset:0 nt
	v_cvt_pk_bf16_f32 v126, v84, v85
	v_cvt_pk_bf16_f32 v127, v86, v87
	global_store_dwordx2 v[130:131], v[126:127], off offset:512 nt
	v_mul_f32_e32 v84, v84, v122
	v_mul_f32_e32 v85, v85, v122
	v_mul_f32_e32 v86, v86, v122
	v_mul_f32_e32 v87, v87, v122
	v_mul_f32_e32 v84, v68, v84
	v_mul_f32_e32 v85, v69, v85
	v_mul_f32_e32 v86, v70, v86
	v_mul_f32_e32 v87, v71, v87
	v_cvt_pk_bf16_f32 v124, v84, v85
	v_cvt_pk_bf16_f32 v125, v86, v87
	global_store_dwordx2 v[128:129], v[124:125], off offset:512 nt
	v_cvt_pk_bf16_f32 v126, v88, v89
	v_cvt_pk_bf16_f32 v127, v90, v91
	global_store_dwordx2 v[130:131], v[126:127], off offset:1024 nt
	v_mul_f32_e32 v88, v88, v122
	v_mul_f32_e32 v89, v89, v122
	v_mul_f32_e32 v90, v90, v122
	v_mul_f32_e32 v91, v91, v122
	v_mul_f32_e32 v88, v72, v88
	v_mul_f32_e32 v89, v73, v89
	v_mul_f32_e32 v90, v74, v90
	v_mul_f32_e32 v91, v75, v91
	v_cvt_pk_bf16_f32 v124, v88, v89
	v_cvt_pk_bf16_f32 v125, v90, v91
	global_store_dwordx2 v[128:129], v[124:125], off offset:1024 nt
	v_cvt_pk_bf16_f32 v126, v92, v93
	v_cvt_pk_bf16_f32 v127, v94, v95
	global_store_dwordx2 v[130:131], v[126:127], off offset:1536 nt
	v_mul_f32_e32 v92, v92, v122
	v_mul_f32_e32 v93, v93, v122
	v_mul_f32_e32 v94, v94, v122
	v_mul_f32_e32 v95, v95, v122
	v_mul_f32_e32 v92, v76, v92
	v_mul_f32_e32 v93, v77, v93
	v_mul_f32_e32 v94, v78, v94
	v_mul_f32_e32 v95, v79, v95
	v_cvt_pk_bf16_f32 v124, v92, v93
	v_cvt_pk_bf16_f32 v125, v94, v95
	global_store_dwordx2 v[128:129], v[124:125], off offset:1536 nt
	v_add_u32_e32 v132, 32, v0
	v_ashrrev_i32_e32 v133, 31, v132
	v_lshlrev_b64 v[138:139], 12, v[132:133]
	v_lshl_add_u64 v[2:3], v[134:135], 0, v[138:139]
	global_load_dwordx4 v[80:83], v[2:3], off offset:0
	global_load_dwordx4 v[84:87], v[2:3], off offset:1024
	global_load_dwordx4 v[88:91], v[2:3], off offset:2048
	global_load_dwordx4 v[92:95], v[2:3], off offset:3072
	v_add_u32_e32 v132, 24, v0
	v_ashrrev_i32_e32 v133, 31, v132
	v_lshlrev_b64 v[138:139], 11, v[132:133]
	v_lshl_add_u64 v[128:129], v[18:19], 0, v[138:139]
	v_lshl_add_u64 v[130:131], v[136:137], 0, v[138:139]
	s_waitcnt vmcnt(12)
	v_mul_f32_e32 v112, v97, v97
	v_mul_f32_e32 v113, v101, v101
	v_mul_f32_e32 v114, v105, v105
	v_mul_f32_e32 v115, v109, v109
	v_fmac_f32_e32 v112, v96, v96
	v_fmac_f32_e32 v113, v100, v100
	v_fmac_f32_e32 v114, v104, v104
	v_fmac_f32_e32 v115, v108, v108
	v_fmac_f32_e32 v112, v98, v98
	v_fmac_f32_e32 v113, v102, v102
	v_fmac_f32_e32 v114, v106, v106
	v_fmac_f32_e32 v115, v110, v110
	v_fmac_f32_e32 v112, v99, v99
	v_fmac_f32_e32 v113, v103, v103
	v_fmac_f32_e32 v114, v107, v107
	v_fmac_f32_e32 v115, v111, v111
	v_add_f32_e32 v116, v112, v113
	v_add_f32_e32 v116, v116, v114
	v_add_f32_e32 v116, v116, v115
	ds_bpermute_b32 v117, v30, v116
	s_waitcnt lgkmcnt(0)
	v_add_f32_e32 v116, v116, v117
	ds_bpermute_b32 v117, v31, v116
	s_waitcnt lgkmcnt(0)
	v_add_f32_e32 v116, v116, v117
	ds_bpermute_b32 v117, v32, v116
	s_waitcnt lgkmcnt(0)
	v_add_f32_e32 v116, v116, v117
	ds_bpermute_b32 v117, v33, v116
	s_waitcnt lgkmcnt(0)
	v_add_f32_e32 v116, v116, v117
	ds_bpermute_b32 v117, v34, v116
	s_waitcnt lgkmcnt(0)
	v_add_f32_e32 v116, v116, v117
	ds_bpermute_b32 v117, v35, v116
	s_waitcnt lgkmcnt(0)
	v_add_f32_e32 v116, v116, v117
	v_fmamk_f32 v116, v116, 0x3a800000, v217
	v_mul_f32_e32 v117, 0x4f800000, v116
	v_cmp_gt_f32_e32 vcc, s36, v116
	s_nop 1
	v_cndmask_b32_e32 v116, v116, v117, vcc
	v_sqrt_f32_e32 v117, v116
	s_nop 0
	v_add_u32_e32 v118, -1, v117
	v_add_u32_e32 v119, 1, v117
	v_fma_f32 v120, -v118, v117, v116
	v_fma_f32 v121, -v119, v117, v116
	v_cmp_ge_f32_e64 s[0:1], 0, v120
	s_nop 1
	v_cndmask_b32_e64 v117, v117, v118, s[0:1]
	v_cmp_lt_f32_e64 s[0:1], 0, v121
	s_nop 1
	v_cndmask_b32_e64 v117, v117, v119, s[0:1]
	v_mul_f32_e32 v118, 0x37800000, v117
	v_cndmask_b32_e32 v117, v117, v118, vcc
	v_cmp_class_f32_e32 vcc, v116, v218
	s_nop 1
	v_cndmask_b32_e32 v116, v117, v116, vcc
	v_div_scale_f32 v117, s[0:1], v116, v116, 1.0
	v_rcp_f32_e32 v119, v117
	v_div_scale_f32 v118, vcc, 1.0, v116, 1.0
	v_fma_f32 v120, -v117, v119, 1.0
	v_fmac_f32_e32 v119, v120, v119
	v_mul_f32_e32 v120, v118, v119
	v_fma_f32 v121, -v117, v120, v118
	v_fmac_f32_e32 v120, v121, v119
	v_fma_f32 v117, -v117, v120, v118
	v_div_fmas_f32 v117, v117, v119, v120
	v_div_fixup_f32 v122, v117, v116, 1.0
	v_cvt_pk_bf16_f32 v126, v96, v97
	v_cvt_pk_bf16_f32 v127, v98, v99
	global_store_dwordx2 v[130:131], v[126:127], off offset:0 nt
	v_mul_f32_e32 v96, v96, v122
	v_mul_f32_e32 v97, v97, v122
	v_mul_f32_e32 v98, v98, v122
	v_mul_f32_e32 v99, v99, v122
	v_mul_f32_e32 v96, v64, v96
	v_mul_f32_e32 v97, v65, v97
	v_mul_f32_e32 v98, v66, v98
	v_mul_f32_e32 v99, v67, v99
	v_cvt_pk_bf16_f32 v124, v96, v97
	v_cvt_pk_bf16_f32 v125, v98, v99
	global_store_dwordx2 v[128:129], v[124:125], off offset:0 nt
	v_cvt_pk_bf16_f32 v126, v100, v101
	v_cvt_pk_bf16_f32 v127, v102, v103
	global_store_dwordx2 v[130:131], v[126:127], off offset:512 nt
	v_mul_f32_e32 v100, v100, v122
	v_mul_f32_e32 v101, v101, v122
	v_mul_f32_e32 v102, v102, v122
	v_mul_f32_e32 v103, v103, v122
	v_mul_f32_e32 v100, v68, v100
	v_mul_f32_e32 v101, v69, v101
	v_mul_f32_e32 v102, v70, v102
	v_mul_f32_e32 v103, v71, v103
	v_cvt_pk_bf16_f32 v124, v100, v101
	v_cvt_pk_bf16_f32 v125, v102, v103
	global_store_dwordx2 v[128:129], v[124:125], off offset:512 nt
	v_cvt_pk_bf16_f32 v126, v104, v105
	v_cvt_pk_bf16_f32 v127, v106, v107
	global_store_dwordx2 v[130:131], v[126:127], off offset:1024 nt
	v_mul_f32_e32 v104, v104, v122
	v_mul_f32_e32 v105, v105, v122
	v_mul_f32_e32 v106, v106, v122
	v_mul_f32_e32 v107, v107, v122
	v_mul_f32_e32 v104, v72, v104
	v_mul_f32_e32 v105, v73, v105
	v_mul_f32_e32 v106, v74, v106
	v_mul_f32_e32 v107, v75, v107
	v_cvt_pk_bf16_f32 v124, v104, v105
	v_cvt_pk_bf16_f32 v125, v106, v107
	global_store_dwordx2 v[128:129], v[124:125], off offset:1024 nt
	v_cvt_pk_bf16_f32 v126, v108, v109
	v_cvt_pk_bf16_f32 v127, v110, v111
	global_store_dwordx2 v[130:131], v[126:127], off offset:1536 nt
	v_mul_f32_e32 v108, v108, v122
	v_mul_f32_e32 v109, v109, v122
	v_mul_f32_e32 v110, v110, v122
	v_mul_f32_e32 v111, v111, v122
	v_mul_f32_e32 v108, v76, v108
	v_mul_f32_e32 v109, v77, v109
	v_mul_f32_e32 v110, v78, v110
	v_mul_f32_e32 v111, v79, v111
	v_cvt_pk_bf16_f32 v124, v108, v109
	v_cvt_pk_bf16_f32 v125, v110, v111
	global_store_dwordx2 v[128:129], v[124:125], off offset:1536 nt
	v_add_u32_e32 v132, 40, v0
	v_ashrrev_i32_e32 v133, 31, v132
	v_lshlrev_b64 v[138:139], 12, v[132:133]
	v_lshl_add_u64 v[2:3], v[134:135], 0, v[138:139]
	global_load_dwordx4 v[96:99], v[2:3], off offset:0
	global_load_dwordx4 v[100:103], v[2:3], off offset:1024
	global_load_dwordx4 v[104:107], v[2:3], off offset:2048
	global_load_dwordx4 v[108:111], v[2:3], off offset:3072
	v_add_u32_e32 v132, 32, v0
	v_ashrrev_i32_e32 v133, 31, v132
	v_lshlrev_b64 v[138:139], 11, v[132:133]
	v_lshl_add_u64 v[128:129], v[18:19], 0, v[138:139]
	v_lshl_add_u64 v[130:131], v[136:137], 0, v[138:139]
	s_waitcnt vmcnt(12)
	v_mul_f32_e32 v112, v81, v81
	v_mul_f32_e32 v113, v85, v85
	v_mul_f32_e32 v114, v89, v89
	v_mul_f32_e32 v115, v93, v93
	v_fmac_f32_e32 v112, v80, v80
	v_fmac_f32_e32 v113, v84, v84
	v_fmac_f32_e32 v114, v88, v88
	v_fmac_f32_e32 v115, v92, v92
	v_fmac_f32_e32 v112, v82, v82
	v_fmac_f32_e32 v113, v86, v86
	v_fmac_f32_e32 v114, v90, v90
	v_fmac_f32_e32 v115, v94, v94
	v_fmac_f32_e32 v112, v83, v83
	v_fmac_f32_e32 v113, v87, v87
	v_fmac_f32_e32 v114, v91, v91
	v_fmac_f32_e32 v115, v95, v95
	v_add_f32_e32 v116, v112, v113
	v_add_f32_e32 v116, v116, v114
	v_add_f32_e32 v116, v116, v115
	ds_bpermute_b32 v117, v30, v116
	s_waitcnt lgkmcnt(0)
	v_add_f32_e32 v116, v116, v117
	ds_bpermute_b32 v117, v31, v116
	s_waitcnt lgkmcnt(0)
	v_add_f32_e32 v116, v116, v117
	ds_bpermute_b32 v117, v32, v116
	s_waitcnt lgkmcnt(0)
	v_add_f32_e32 v116, v116, v117
	ds_bpermute_b32 v117, v33, v116
	s_waitcnt lgkmcnt(0)
	v_add_f32_e32 v116, v116, v117
	ds_bpermute_b32 v117, v34, v116
	s_waitcnt lgkmcnt(0)
	v_add_f32_e32 v116, v116, v117
	ds_bpermute_b32 v117, v35, v116
	s_waitcnt lgkmcnt(0)
	v_add_f32_e32 v116, v116, v117
	v_fmamk_f32 v116, v116, 0x3a800000, v217
	v_mul_f32_e32 v117, 0x4f800000, v116
	v_cmp_gt_f32_e32 vcc, s36, v116
	s_nop 1
	v_cndmask_b32_e32 v116, v116, v117, vcc
	v_sqrt_f32_e32 v117, v116
	s_nop 0
	v_add_u32_e32 v118, -1, v117
	v_add_u32_e32 v119, 1, v117
	v_fma_f32 v120, -v118, v117, v116
	v_fma_f32 v121, -v119, v117, v116
	v_cmp_ge_f32_e64 s[0:1], 0, v120
	s_nop 1
	v_cndmask_b32_e64 v117, v117, v118, s[0:1]
	v_cmp_lt_f32_e64 s[0:1], 0, v121
	s_nop 1
	v_cndmask_b32_e64 v117, v117, v119, s[0:1]
	v_mul_f32_e32 v118, 0x37800000, v117
	v_cndmask_b32_e32 v117, v117, v118, vcc
	v_cmp_class_f32_e32 vcc, v116, v218
	s_nop 1
	v_cndmask_b32_e32 v116, v117, v116, vcc
	v_div_scale_f32 v117, s[0:1], v116, v116, 1.0
	v_rcp_f32_e32 v119, v117
	v_div_scale_f32 v118, vcc, 1.0, v116, 1.0
	v_fma_f32 v120, -v117, v119, 1.0
	v_fmac_f32_e32 v119, v120, v119
	v_mul_f32_e32 v120, v118, v119
	v_fma_f32 v121, -v117, v120, v118
	v_fmac_f32_e32 v120, v121, v119
	v_fma_f32 v117, -v117, v120, v118
	v_div_fmas_f32 v117, v117, v119, v120
	v_div_fixup_f32 v122, v117, v116, 1.0
	v_cvt_pk_bf16_f32 v126, v80, v81
	v_cvt_pk_bf16_f32 v127, v82, v83
	global_store_dwordx2 v[130:131], v[126:127], off offset:0 nt
	v_mul_f32_e32 v80, v80, v122
	v_mul_f32_e32 v81, v81, v122
	v_mul_f32_e32 v82, v82, v122
	v_mul_f32_e32 v83, v83, v122
	v_mul_f32_e32 v80, v64, v80
	v_mul_f32_e32 v81, v65, v81
	v_mul_f32_e32 v82, v66, v82
	v_mul_f32_e32 v83, v67, v83
	v_cvt_pk_bf16_f32 v124, v80, v81
	v_cvt_pk_bf16_f32 v125, v82, v83
	global_store_dwordx2 v[128:129], v[124:125], off offset:0 nt
	v_cvt_pk_bf16_f32 v126, v84, v85
	v_cvt_pk_bf16_f32 v127, v86, v87
	global_store_dwordx2 v[130:131], v[126:127], off offset:512 nt
	v_mul_f32_e32 v84, v84, v122
	v_mul_f32_e32 v85, v85, v122
	v_mul_f32_e32 v86, v86, v122
	v_mul_f32_e32 v87, v87, v122
	v_mul_f32_e32 v84, v68, v84
	v_mul_f32_e32 v85, v69, v85
	v_mul_f32_e32 v86, v70, v86
	v_mul_f32_e32 v87, v71, v87
	v_cvt_pk_bf16_f32 v124, v84, v85
	v_cvt_pk_bf16_f32 v125, v86, v87
	global_store_dwordx2 v[128:129], v[124:125], off offset:512 nt
	v_cvt_pk_bf16_f32 v126, v88, v89
	v_cvt_pk_bf16_f32 v127, v90, v91
	global_store_dwordx2 v[130:131], v[126:127], off offset:1024 nt
	v_mul_f32_e32 v88, v88, v122
	v_mul_f32_e32 v89, v89, v122
	v_mul_f32_e32 v90, v90, v122
	v_mul_f32_e32 v91, v91, v122
	v_mul_f32_e32 v88, v72, v88
	v_mul_f32_e32 v89, v73, v89
	v_mul_f32_e32 v90, v74, v90
	v_mul_f32_e32 v91, v75, v91
	v_cvt_pk_bf16_f32 v124, v88, v89
	v_cvt_pk_bf16_f32 v125, v90, v91
	global_store_dwordx2 v[128:129], v[124:125], off offset:1024 nt
	v_cvt_pk_bf16_f32 v126, v92, v93
	v_cvt_pk_bf16_f32 v127, v94, v95
	global_store_dwordx2 v[130:131], v[126:127], off offset:1536 nt
	v_mul_f32_e32 v92, v92, v122
	v_mul_f32_e32 v93, v93, v122
	v_mul_f32_e32 v94, v94, v122
	v_mul_f32_e32 v95, v95, v122
	v_mul_f32_e32 v92, v76, v92
	v_mul_f32_e32 v93, v77, v93
	v_mul_f32_e32 v94, v78, v94
	v_mul_f32_e32 v95, v79, v95
	v_cvt_pk_bf16_f32 v124, v92, v93
	v_cvt_pk_bf16_f32 v125, v94, v95
	global_store_dwordx2 v[128:129], v[124:125], off offset:1536 nt
	v_add_u32_e32 v132, 48, v0
	v_ashrrev_i32_e32 v133, 31, v132
	v_lshlrev_b64 v[138:139], 12, v[132:133]
	v_lshl_add_u64 v[2:3], v[134:135], 0, v[138:139]
	global_load_dwordx4 v[80:83], v[2:3], off offset:0
	global_load_dwordx4 v[84:87], v[2:3], off offset:1024
	global_load_dwordx4 v[88:91], v[2:3], off offset:2048
	global_load_dwordx4 v[92:95], v[2:3], off offset:3072
	v_add_u32_e32 v132, 40, v0
	v_ashrrev_i32_e32 v133, 31, v132
	v_lshlrev_b64 v[138:139], 11, v[132:133]
	v_lshl_add_u64 v[128:129], v[18:19], 0, v[138:139]
	v_lshl_add_u64 v[130:131], v[136:137], 0, v[138:139]
	s_waitcnt vmcnt(12)
	v_mul_f32_e32 v112, v97, v97
	v_mul_f32_e32 v113, v101, v101
	v_mul_f32_e32 v114, v105, v105
	v_mul_f32_e32 v115, v109, v109
	v_fmac_f32_e32 v112, v96, v96
	v_fmac_f32_e32 v113, v100, v100
	v_fmac_f32_e32 v114, v104, v104
	v_fmac_f32_e32 v115, v108, v108
	v_fmac_f32_e32 v112, v98, v98
	v_fmac_f32_e32 v113, v102, v102
	v_fmac_f32_e32 v114, v106, v106
	v_fmac_f32_e32 v115, v110, v110
	v_fmac_f32_e32 v112, v99, v99
	v_fmac_f32_e32 v113, v103, v103
	v_fmac_f32_e32 v114, v107, v107
	v_fmac_f32_e32 v115, v111, v111
	v_add_f32_e32 v116, v112, v113
	v_add_f32_e32 v116, v116, v114
	v_add_f32_e32 v116, v116, v115
	ds_bpermute_b32 v117, v30, v116
	s_waitcnt lgkmcnt(0)
	v_add_f32_e32 v116, v116, v117
	ds_bpermute_b32 v117, v31, v116
	s_waitcnt lgkmcnt(0)
	v_add_f32_e32 v116, v116, v117
	ds_bpermute_b32 v117, v32, v116
	s_waitcnt lgkmcnt(0)
	v_add_f32_e32 v116, v116, v117
	ds_bpermute_b32 v117, v33, v116
	s_waitcnt lgkmcnt(0)
	v_add_f32_e32 v116, v116, v117
	ds_bpermute_b32 v117, v34, v116
	s_waitcnt lgkmcnt(0)
	v_add_f32_e32 v116, v116, v117
	ds_bpermute_b32 v117, v35, v116
	s_waitcnt lgkmcnt(0)
	v_add_f32_e32 v116, v116, v117
	v_fmamk_f32 v116, v116, 0x3a800000, v217
	v_mul_f32_e32 v117, 0x4f800000, v116
	v_cmp_gt_f32_e32 vcc, s36, v116
	s_nop 1
	v_cndmask_b32_e32 v116, v116, v117, vcc
	v_sqrt_f32_e32 v117, v116
	s_nop 0
	v_add_u32_e32 v118, -1, v117
	v_add_u32_e32 v119, 1, v117
	v_fma_f32 v120, -v118, v117, v116
	v_fma_f32 v121, -v119, v117, v116
	v_cmp_ge_f32_e64 s[0:1], 0, v120
	s_nop 1
	v_cndmask_b32_e64 v117, v117, v118, s[0:1]
	v_cmp_lt_f32_e64 s[0:1], 0, v121
	s_nop 1
	v_cndmask_b32_e64 v117, v117, v119, s[0:1]
	v_mul_f32_e32 v118, 0x37800000, v117
	v_cndmask_b32_e32 v117, v117, v118, vcc
	v_cmp_class_f32_e32 vcc, v116, v218
	s_nop 1
	v_cndmask_b32_e32 v116, v117, v116, vcc
	v_div_scale_f32 v117, s[0:1], v116, v116, 1.0
	v_rcp_f32_e32 v119, v117
	v_div_scale_f32 v118, vcc, 1.0, v116, 1.0
	v_fma_f32 v120, -v117, v119, 1.0
	v_fmac_f32_e32 v119, v120, v119
	v_mul_f32_e32 v120, v118, v119
	v_fma_f32 v121, -v117, v120, v118
	v_fmac_f32_e32 v120, v121, v119
	v_fma_f32 v117, -v117, v120, v118
	v_div_fmas_f32 v117, v117, v119, v120
	v_div_fixup_f32 v122, v117, v116, 1.0
	v_cvt_pk_bf16_f32 v126, v96, v97
	v_cvt_pk_bf16_f32 v127, v98, v99
	global_store_dwordx2 v[130:131], v[126:127], off offset:0 nt
	v_mul_f32_e32 v96, v96, v122
	v_mul_f32_e32 v97, v97, v122
	v_mul_f32_e32 v98, v98, v122
	v_mul_f32_e32 v99, v99, v122
	v_mul_f32_e32 v96, v64, v96
	v_mul_f32_e32 v97, v65, v97
	v_mul_f32_e32 v98, v66, v98
	v_mul_f32_e32 v99, v67, v99
	v_cvt_pk_bf16_f32 v124, v96, v97
	v_cvt_pk_bf16_f32 v125, v98, v99
	global_store_dwordx2 v[128:129], v[124:125], off offset:0 nt
	v_cvt_pk_bf16_f32 v126, v100, v101
	v_cvt_pk_bf16_f32 v127, v102, v103
	global_store_dwordx2 v[130:131], v[126:127], off offset:512 nt
	v_mul_f32_e32 v100, v100, v122
	v_mul_f32_e32 v101, v101, v122
	v_mul_f32_e32 v102, v102, v122
	v_mul_f32_e32 v103, v103, v122
	v_mul_f32_e32 v100, v68, v100
	v_mul_f32_e32 v101, v69, v101
	v_mul_f32_e32 v102, v70, v102
	v_mul_f32_e32 v103, v71, v103
	v_cvt_pk_bf16_f32 v124, v100, v101
	v_cvt_pk_bf16_f32 v125, v102, v103
	global_store_dwordx2 v[128:129], v[124:125], off offset:512 nt
	v_cvt_pk_bf16_f32 v126, v104, v105
	v_cvt_pk_bf16_f32 v127, v106, v107
	global_store_dwordx2 v[130:131], v[126:127], off offset:1024 nt
	v_mul_f32_e32 v104, v104, v122
	v_mul_f32_e32 v105, v105, v122
	v_mul_f32_e32 v106, v106, v122
	v_mul_f32_e32 v107, v107, v122
	v_mul_f32_e32 v104, v72, v104
	v_mul_f32_e32 v105, v73, v105
	v_mul_f32_e32 v106, v74, v106
	v_mul_f32_e32 v107, v75, v107
	v_cvt_pk_bf16_f32 v124, v104, v105
	v_cvt_pk_bf16_f32 v125, v106, v107
	global_store_dwordx2 v[128:129], v[124:125], off offset:1024 nt
	v_cvt_pk_bf16_f32 v126, v108, v109
	v_cvt_pk_bf16_f32 v127, v110, v111
	global_store_dwordx2 v[130:131], v[126:127], off offset:1536 nt
	v_mul_f32_e32 v108, v108, v122
	v_mul_f32_e32 v109, v109, v122
	v_mul_f32_e32 v110, v110, v122
	v_mul_f32_e32 v111, v111, v122
	v_mul_f32_e32 v108, v76, v108
	v_mul_f32_e32 v109, v77, v109
	v_mul_f32_e32 v110, v78, v110
	v_mul_f32_e32 v111, v79, v111
	v_cvt_pk_bf16_f32 v124, v108, v109
	v_cvt_pk_bf16_f32 v125, v110, v111
	global_store_dwordx2 v[128:129], v[124:125], off offset:1536 nt
	v_add_u32_e32 v132, 56, v0
	v_ashrrev_i32_e32 v133, 31, v132
	v_lshlrev_b64 v[138:139], 12, v[132:133]
	v_lshl_add_u64 v[2:3], v[134:135], 0, v[138:139]
	global_load_dwordx4 v[96:99], v[2:3], off offset:0
	global_load_dwordx4 v[100:103], v[2:3], off offset:1024
	global_load_dwordx4 v[104:107], v[2:3], off offset:2048
	global_load_dwordx4 v[108:111], v[2:3], off offset:3072
	v_add_u32_e32 v132, 48, v0
	v_ashrrev_i32_e32 v133, 31, v132
	v_lshlrev_b64 v[138:139], 11, v[132:133]
	v_lshl_add_u64 v[128:129], v[18:19], 0, v[138:139]
	v_lshl_add_u64 v[130:131], v[136:137], 0, v[138:139]
	s_waitcnt vmcnt(12)
	v_mul_f32_e32 v112, v81, v81
	v_mul_f32_e32 v113, v85, v85
	v_mul_f32_e32 v114, v89, v89
	v_mul_f32_e32 v115, v93, v93
	v_fmac_f32_e32 v112, v80, v80
	v_fmac_f32_e32 v113, v84, v84
	v_fmac_f32_e32 v114, v88, v88
	v_fmac_f32_e32 v115, v92, v92
	v_fmac_f32_e32 v112, v82, v82
	v_fmac_f32_e32 v113, v86, v86
	v_fmac_f32_e32 v114, v90, v90
	v_fmac_f32_e32 v115, v94, v94
	v_fmac_f32_e32 v112, v83, v83
	v_fmac_f32_e32 v113, v87, v87
	v_fmac_f32_e32 v114, v91, v91
	v_fmac_f32_e32 v115, v95, v95
	v_add_f32_e32 v116, v112, v113
	v_add_f32_e32 v116, v116, v114
	v_add_f32_e32 v116, v116, v115
	ds_bpermute_b32 v117, v30, v116
	s_waitcnt lgkmcnt(0)
	v_add_f32_e32 v116, v116, v117
	ds_bpermute_b32 v117, v31, v116
	s_waitcnt lgkmcnt(0)
	v_add_f32_e32 v116, v116, v117
	ds_bpermute_b32 v117, v32, v116
	s_waitcnt lgkmcnt(0)
	v_add_f32_e32 v116, v116, v117
	ds_bpermute_b32 v117, v33, v116
	s_waitcnt lgkmcnt(0)
	v_add_f32_e32 v116, v116, v117
	ds_bpermute_b32 v117, v34, v116
	s_waitcnt lgkmcnt(0)
	v_add_f32_e32 v116, v116, v117
	ds_bpermute_b32 v117, v35, v116
	s_waitcnt lgkmcnt(0)
	v_add_f32_e32 v116, v116, v117
	v_fmamk_f32 v116, v116, 0x3a800000, v217
	v_mul_f32_e32 v117, 0x4f800000, v116
	v_cmp_gt_f32_e32 vcc, s36, v116
	s_nop 1
	v_cndmask_b32_e32 v116, v116, v117, vcc
	v_sqrt_f32_e32 v117, v116
	s_nop 0
	v_add_u32_e32 v118, -1, v117
	v_add_u32_e32 v119, 1, v117
	v_fma_f32 v120, -v118, v117, v116
	v_fma_f32 v121, -v119, v117, v116
	v_cmp_ge_f32_e64 s[0:1], 0, v120
	s_nop 1
	v_cndmask_b32_e64 v117, v117, v118, s[0:1]
	v_cmp_lt_f32_e64 s[0:1], 0, v121
	s_nop 1
	v_cndmask_b32_e64 v117, v117, v119, s[0:1]
	v_mul_f32_e32 v118, 0x37800000, v117
	v_cndmask_b32_e32 v117, v117, v118, vcc
	v_cmp_class_f32_e32 vcc, v116, v218
	s_nop 1
	v_cndmask_b32_e32 v116, v117, v116, vcc
	v_div_scale_f32 v117, s[0:1], v116, v116, 1.0
	v_rcp_f32_e32 v119, v117
	v_div_scale_f32 v118, vcc, 1.0, v116, 1.0
	v_fma_f32 v120, -v117, v119, 1.0
	v_fmac_f32_e32 v119, v120, v119
	v_mul_f32_e32 v120, v118, v119
	v_fma_f32 v121, -v117, v120, v118
	v_fmac_f32_e32 v120, v121, v119
	v_fma_f32 v117, -v117, v120, v118
	v_div_fmas_f32 v117, v117, v119, v120
	v_div_fixup_f32 v122, v117, v116, 1.0
	v_cvt_pk_bf16_f32 v126, v80, v81
	v_cvt_pk_bf16_f32 v127, v82, v83
	global_store_dwordx2 v[130:131], v[126:127], off offset:0 nt
	v_mul_f32_e32 v80, v80, v122
	v_mul_f32_e32 v81, v81, v122
	v_mul_f32_e32 v82, v82, v122
	v_mul_f32_e32 v83, v83, v122
	v_mul_f32_e32 v80, v64, v80
	v_mul_f32_e32 v81, v65, v81
	v_mul_f32_e32 v82, v66, v82
	v_mul_f32_e32 v83, v67, v83
	v_cvt_pk_bf16_f32 v124, v80, v81
	v_cvt_pk_bf16_f32 v125, v82, v83
	global_store_dwordx2 v[128:129], v[124:125], off offset:0 nt
	v_cvt_pk_bf16_f32 v126, v84, v85
	v_cvt_pk_bf16_f32 v127, v86, v87
	global_store_dwordx2 v[130:131], v[126:127], off offset:512 nt
	v_mul_f32_e32 v84, v84, v122
	v_mul_f32_e32 v85, v85, v122
	v_mul_f32_e32 v86, v86, v122
	v_mul_f32_e32 v87, v87, v122
	v_mul_f32_e32 v84, v68, v84
	v_mul_f32_e32 v85, v69, v85
	v_mul_f32_e32 v86, v70, v86
	v_mul_f32_e32 v87, v71, v87
	v_cvt_pk_bf16_f32 v124, v84, v85
	v_cvt_pk_bf16_f32 v125, v86, v87
	global_store_dwordx2 v[128:129], v[124:125], off offset:512 nt
	v_cvt_pk_bf16_f32 v126, v88, v89
	v_cvt_pk_bf16_f32 v127, v90, v91
	global_store_dwordx2 v[130:131], v[126:127], off offset:1024 nt
	v_mul_f32_e32 v88, v88, v122
	v_mul_f32_e32 v89, v89, v122
	v_mul_f32_e32 v90, v90, v122
	v_mul_f32_e32 v91, v91, v122
	v_mul_f32_e32 v88, v72, v88
	v_mul_f32_e32 v89, v73, v89
	v_mul_f32_e32 v90, v74, v90
	v_mul_f32_e32 v91, v75, v91
	v_cvt_pk_bf16_f32 v124, v88, v89
	v_cvt_pk_bf16_f32 v125, v90, v91
	global_store_dwordx2 v[128:129], v[124:125], off offset:1024 nt
	v_cvt_pk_bf16_f32 v126, v92, v93
	v_cvt_pk_bf16_f32 v127, v94, v95
	global_store_dwordx2 v[130:131], v[126:127], off offset:1536 nt
	v_mul_f32_e32 v92, v92, v122
	v_mul_f32_e32 v93, v93, v122
	v_mul_f32_e32 v94, v94, v122
	v_mul_f32_e32 v95, v95, v122
	v_mul_f32_e32 v92, v76, v92
	v_mul_f32_e32 v93, v77, v93
	v_mul_f32_e32 v94, v78, v94
	v_mul_f32_e32 v95, v79, v95
	v_cvt_pk_bf16_f32 v124, v92, v93
	v_cvt_pk_bf16_f32 v125, v94, v95
	global_store_dwordx2 v[128:129], v[124:125], off offset:1536 nt
	v_add_u32_e32 v132, 56, v0
	v_ashrrev_i32_e32 v133, 31, v132
	v_lshlrev_b64 v[138:139], 11, v[132:133]
	v_lshl_add_u64 v[128:129], v[18:19], 0, v[138:139]
	v_lshl_add_u64 v[130:131], v[136:137], 0, v[138:139]
	s_waitcnt vmcnt(8)
	v_mul_f32_e32 v112, v97, v97
	v_mul_f32_e32 v113, v101, v101
	v_mul_f32_e32 v114, v105, v105
	v_mul_f32_e32 v115, v109, v109
	v_fmac_f32_e32 v112, v96, v96
	v_fmac_f32_e32 v113, v100, v100
	v_fmac_f32_e32 v114, v104, v104
	v_fmac_f32_e32 v115, v108, v108
	v_fmac_f32_e32 v112, v98, v98
	v_fmac_f32_e32 v113, v102, v102
	v_fmac_f32_e32 v114, v106, v106
	v_fmac_f32_e32 v115, v110, v110
	v_fmac_f32_e32 v112, v99, v99
	v_fmac_f32_e32 v113, v103, v103
	v_fmac_f32_e32 v114, v107, v107
	v_fmac_f32_e32 v115, v111, v111
	v_add_f32_e32 v116, v112, v113
	v_add_f32_e32 v116, v116, v114
	v_add_f32_e32 v116, v116, v115
	ds_bpermute_b32 v117, v30, v116
	s_waitcnt lgkmcnt(0)
	v_add_f32_e32 v116, v116, v117
	ds_bpermute_b32 v117, v31, v116
	s_waitcnt lgkmcnt(0)
	v_add_f32_e32 v116, v116, v117
	ds_bpermute_b32 v117, v32, v116
	s_waitcnt lgkmcnt(0)
	v_add_f32_e32 v116, v116, v117
	ds_bpermute_b32 v117, v33, v116
	s_waitcnt lgkmcnt(0)
	v_add_f32_e32 v116, v116, v117
	ds_bpermute_b32 v117, v34, v116
	s_waitcnt lgkmcnt(0)
	v_add_f32_e32 v116, v116, v117
	ds_bpermute_b32 v117, v35, v116
	s_waitcnt lgkmcnt(0)
	v_add_f32_e32 v116, v116, v117
	v_fmamk_f32 v116, v116, 0x3a800000, v217
	v_mul_f32_e32 v117, 0x4f800000, v116
	v_cmp_gt_f32_e32 vcc, s36, v116
	s_nop 1
	v_cndmask_b32_e32 v116, v116, v117, vcc
	v_sqrt_f32_e32 v117, v116
	s_nop 0
	v_add_u32_e32 v118, -1, v117
	v_add_u32_e32 v119, 1, v117
	v_fma_f32 v120, -v118, v117, v116
	v_fma_f32 v121, -v119, v117, v116
	v_cmp_ge_f32_e64 s[0:1], 0, v120
	s_nop 1
	v_cndmask_b32_e64 v117, v117, v118, s[0:1]
	v_cmp_lt_f32_e64 s[0:1], 0, v121
	s_nop 1
	v_cndmask_b32_e64 v117, v117, v119, s[0:1]
	v_mul_f32_e32 v118, 0x37800000, v117
	v_cndmask_b32_e32 v117, v117, v118, vcc
	v_cmp_class_f32_e32 vcc, v116, v218
	s_nop 1
	v_cndmask_b32_e32 v116, v117, v116, vcc
	v_div_scale_f32 v117, s[0:1], v116, v116, 1.0
	v_rcp_f32_e32 v119, v117
	v_div_scale_f32 v118, vcc, 1.0, v116, 1.0
	v_fma_f32 v120, -v117, v119, 1.0
	v_fmac_f32_e32 v119, v120, v119
	v_mul_f32_e32 v120, v118, v119
	v_fma_f32 v121, -v117, v120, v118
	v_fmac_f32_e32 v120, v121, v119
	v_fma_f32 v117, -v117, v120, v118
	v_div_fmas_f32 v117, v117, v119, v120
	v_div_fixup_f32 v122, v117, v116, 1.0
	v_cvt_pk_bf16_f32 v126, v96, v97
	v_cvt_pk_bf16_f32 v127, v98, v99
	global_store_dwordx2 v[130:131], v[126:127], off offset:0 nt
	v_mul_f32_e32 v96, v96, v122
	v_mul_f32_e32 v97, v97, v122
	v_mul_f32_e32 v98, v98, v122
	v_mul_f32_e32 v99, v99, v122
	v_mul_f32_e32 v96, v64, v96
	v_mul_f32_e32 v97, v65, v97
	v_mul_f32_e32 v98, v66, v98
	v_mul_f32_e32 v99, v67, v99
	v_cvt_pk_bf16_f32 v124, v96, v97
	v_cvt_pk_bf16_f32 v125, v98, v99
	global_store_dwordx2 v[128:129], v[124:125], off offset:0 nt
	v_cvt_pk_bf16_f32 v126, v100, v101
	v_cvt_pk_bf16_f32 v127, v102, v103
	global_store_dwordx2 v[130:131], v[126:127], off offset:512 nt
	v_mul_f32_e32 v100, v100, v122
	v_mul_f32_e32 v101, v101, v122
	v_mul_f32_e32 v102, v102, v122
	v_mul_f32_e32 v103, v103, v122
	v_mul_f32_e32 v100, v68, v100
	v_mul_f32_e32 v101, v69, v101
	v_mul_f32_e32 v102, v70, v102
	v_mul_f32_e32 v103, v71, v103
	v_cvt_pk_bf16_f32 v124, v100, v101
	v_cvt_pk_bf16_f32 v125, v102, v103
	global_store_dwordx2 v[128:129], v[124:125], off offset:512 nt
	v_cvt_pk_bf16_f32 v126, v104, v105
	v_cvt_pk_bf16_f32 v127, v106, v107
	global_store_dwordx2 v[130:131], v[126:127], off offset:1024 nt
	v_mul_f32_e32 v104, v104, v122
	v_mul_f32_e32 v105, v105, v122
	v_mul_f32_e32 v106, v106, v122
	v_mul_f32_e32 v107, v107, v122
	v_mul_f32_e32 v104, v72, v104
	v_mul_f32_e32 v105, v73, v105
	v_mul_f32_e32 v106, v74, v106
	v_mul_f32_e32 v107, v75, v107
	v_cvt_pk_bf16_f32 v124, v104, v105
	v_cvt_pk_bf16_f32 v125, v106, v107
	global_store_dwordx2 v[128:129], v[124:125], off offset:1024 nt
	v_cvt_pk_bf16_f32 v126, v108, v109
	v_cvt_pk_bf16_f32 v127, v110, v111
	global_store_dwordx2 v[130:131], v[126:127], off offset:1536 nt
	v_mul_f32_e32 v108, v108, v122
	v_mul_f32_e32 v109, v109, v122
	v_mul_f32_e32 v110, v110, v122
	v_mul_f32_e32 v111, v111, v122
	v_mul_f32_e32 v108, v76, v108
	v_mul_f32_e32 v109, v77, v109
	v_mul_f32_e32 v110, v78, v110
	v_mul_f32_e32 v111, v79, v111
	v_cvt_pk_bf16_f32 v124, v108, v109
	v_cvt_pk_bf16_f32 v125, v110, v111
	global_store_dwordx2 v[128:129], v[124:125], off offset:1536 nt
	s_mov_b32 s2, 64
